# K-loop: barrier ending each MFMA segment signalled one MFMA early, trailing MFMA at raised priority (on best)
# speedup vs baseline: 1.0031x; 1.0031x over previous
; #define PG8_STAGE(bufoff, gbase, voff) do { _Pragma("unroll") for (int _i = 0; _i < 2; ++_i) \
;         __builtin_amdgcn_global_load_lds((const unsigned*)((const char*)(gbase) + (voff)[_i]), (PG8_LAS unsigned*)(lds + (bufoff) + ldsw + _i * 8192), 16, 0, 0); } while (0)
; #define PG8_LDA(dst, b, h) do { _Pragma("unroll") for (int m = 0; m < 4; ++m) _Pragma("unroll") for (int k = 0; k < 2; ++k) dst[m][k] = *(const PG8_LAS bf16x8*)(lds + PG8_SA(b, h) + aoff + m * 2048 + k * 1024); } while (0)
; #define PG8_LDB(dst, b, h) do { _Pragma("unroll") for (int n = 0; n < 2; ++n) _Pragma("unroll") for (int k = 0; k < 2; ++k) dst[n][k] = *(const PG8_LAS bf16x8*)(lds + PG8_SB(b, h) + boff + n * 2048 + k * 1024); } while (0)
; #define PG8_MMA(ai, bj, At, Bt) do { __builtin_amdgcn_s_setprio(1); _Pragma("unroll") for (int m = 0; m < 4; ++m) _Pragma("unroll") for (int n = 0; n < 2; ++n) _Pragma("unroll") for (int k = 0; k < 2; ++k) \
;         acc[ai][bj][m][n] = __builtin_amdgcn_mfma_f32_16x16x32_bf16(Bt[n][k], At[m][k], acc[ai][bj][m][n], 0, 0, 0); __builtin_amdgcn_s_setprio(0); } while (0)
; #define PG8_WAIT_V(n) asm volatile("s_waitcnt vmcnt(" #n ")" ::: "memory")
; #define PG8_BAR __builtin_amdgcn_s_barrier()
; template <class Epi, class Sched, bool ALIGN_EPI = false, bool SP2 = false>
; __device__ __forceinline__ void gemm_phase(PG8_LAS unsigned char* lds, const Gemm g, const Sched& S, const Epi& E) {
;     ...
;         for (int t = 0; t < nt; t += 2) {
;             const bool last = (t == nt - 2);
;             const char* a1 = cA + (size_t)(t + 1) * kstep;
;             const char* a2 = last ? nA : cA + (size_t)(t + 2) * kstep; const char* b2 = last ? nB : cB + (size_t)(t + 2) * kstep;
;             const char* a3 = a2 + kstep; const char* b3 = b2 + kstep;
;             if (last && has_next) S.a_ready(nxt);
;             if constexpr (SP2) {
;             PG8_LDB(B0, 0, 0); PG8_LDB(B1, 0, 1); PG8_SCHED; PG8_LDA(At, 0, 0); PG8_STAGE(PG8_SA(1, 1), a1 + hstep, voffA);
;             PG8_WAIT_V(8); PG8_WAIT_L(0); PG8_BAR; PG8_MMA(0, 0, At, B0); PG8_MMA(0, 1, At, B1); PG8_BAR; PG8_SCHED;
;             PG8_LDA(At, 0, 1); PG8_STAGE(PG8_SB(0, 0), b2, voffB); PG8_STAGE(PG8_SB(0, 1), b2 + hstep, voffB); PG8_STAGE(PG8_SA(0, 0), a2, voffA);
;             PG8_WAIT_V(8); PG8_WAIT_L(0); PG8_BAR; PG8_MMA(1, 0, At, B0); PG8_MMA(1, 1, At, B1); PG8_BAR; PG8_SCHED;
.LBB0_166:
	s_add_u32 s24, s22, 0xfffc0080
	s_addc_u32 s25, s23, -1
	s_add_i32 s59, 0, 0x10000
	s_cmp_eq_u32 s58, 12
	s_cselect_b32 s27, s11, s25
	s_cselect_b32 s26, s15, s24
	v_add_u32_e32 v0, s59, v202
	s_cselect_b32 s25, s13, s57
	s_cselect_b32 s24, s21, s56
	s_add_i32 s62, 0, 0x14000
	ds_read_b128 v[130:133], v0
	ds_read_b128 v[134:137], v0 offset:1024
	ds_read_b128 v[138:141], v0 offset:2048
	ds_read_b128 v[142:145], v0 offset:3072
	v_add_u32_e32 v0, s62, v202
	ds_read_b128 v[146:149], v0
	ds_read_b128 v[162:165], v0 offset:1024
	ds_read_b128 v[192:195], v0 offset:2048
	ds_read_b128 v[196:199], v0 offset:3072
	v_lshl_add_u64 v[200:201], s[22:23], 0, v[160:161]
	s_add_i32 m0, s38, 0xc000
	ds_read_b128 v[206:209], v204
	ds_read_b128 v[210:213], v204 offset:1024
	ds_read_b128 v[214:217], v204 offset:2048
	ds_read_b128 v[218:221], v204 offset:3072
	ds_read_b128 v[222:225], v204 offset:4096
	ds_read_b128 v[226:229], v204 offset:5120
	ds_read_b128 v[230:233], v204 offset:6144
	ds_read_b128 v[244:247], v204 offset:7168
	global_load_lds_dwordx4 v[200:201], off
	v_lshl_add_u64 v[200:201], s[22:23], 0, v[158:159]
	s_add_i32 m0, s38, 0xe000
	s_nop 0
	global_load_lds_dwordx4 v[200:201], off
	s_waitcnt vmcnt(8)
	s_waitcnt lgkmcnt(0)
	s_barrier
	s_setprio 1
	s_waitcnt lgkmcnt(0)
	v_mfma_f32_16x16x32_bf16 v[126:129], v[130:133], v[206:209], v[126:129]
	v_mfma_f32_16x16x32_bf16 v[122:125], v[138:141], v[206:209], v[122:125]
	v_mfma_f32_16x16x32_bf16 v[110:113], v[130:133], v[214:217], v[110:113]
	v_mfma_f32_16x16x32_bf16 v[106:109], v[138:141], v[214:217], v[106:109]
	v_mfma_f32_16x16x32_bf16 v[94:97], v[130:133], v[222:225], v[94:97]
	v_mfma_f32_16x16x32_bf16 v[90:93], v[138:141], v[222:225], v[90:93]
	v_mfma_f32_16x16x32_bf16 v[78:81], v[130:133], v[230:233], v[78:81]
	v_mfma_f32_16x16x32_bf16 v[74:77], v[138:141], v[230:233], v[74:77]
	v_mfma_f32_16x16x32_bf16 v[126:129], v[134:137], v[210:213], v[126:129]
	v_mfma_f32_16x16x32_bf16 v[122:125], v[142:145], v[210:213], v[122:125]
	v_mfma_f32_16x16x32_bf16 v[110:113], v[134:137], v[218:221], v[110:113]
	v_mfma_f32_16x16x32_bf16 v[106:109], v[142:145], v[218:221], v[106:109]
	v_mfma_f32_16x16x32_bf16 v[94:97], v[134:137], v[226:229], v[94:97]
	v_mfma_f32_16x16x32_bf16 v[90:93], v[142:145], v[226:229], v[90:93]
	v_mfma_f32_16x16x32_bf16 v[78:81], v[134:137], v[244:247], v[78:81]
	v_mfma_f32_16x16x32_bf16 v[74:77], v[142:145], v[244:247], v[74:77]
	s_setprio 0
	s_setprio 1
	v_mfma_f32_16x16x32_bf16 v[118:121], v[146:149], v[206:209], v[118:121]
	v_mfma_f32_16x16x32_bf16 v[114:117], v[192:195], v[206:209], v[114:117]
	v_mfma_f32_16x16x32_bf16 v[102:105], v[146:149], v[214:217], v[102:105]
	v_mfma_f32_16x16x32_bf16 v[98:101], v[192:195], v[214:217], v[98:101]
	v_mfma_f32_16x16x32_bf16 v[86:89], v[146:149], v[222:225], v[86:89]
	v_mfma_f32_16x16x32_bf16 v[82:85], v[192:195], v[222:225], v[82:85]
	v_mfma_f32_16x16x32_bf16 v[70:73], v[146:149], v[230:233], v[70:73]
	v_mfma_f32_16x16x32_bf16 v[66:69], v[192:195], v[230:233], v[66:69]
	v_mfma_f32_16x16x32_bf16 v[118:121], v[162:165], v[210:213], v[118:121]
	v_mfma_f32_16x16x32_bf16 v[114:117], v[196:199], v[210:213], v[114:117]
	v_mfma_f32_16x16x32_bf16 v[102:105], v[162:165], v[218:221], v[102:105]
	v_mfma_f32_16x16x32_bf16 v[98:101], v[196:199], v[218:221], v[98:101]
	v_mfma_f32_16x16x32_bf16 v[86:89], v[162:165], v[226:229], v[86:89]
	v_mfma_f32_16x16x32_bf16 v[82:85], v[196:199], v[226:229], v[82:85]
	v_mfma_f32_16x16x32_bf16 v[70:73], v[162:165], v[244:247], v[70:73]
	s_setprio 3
	s_barrier
	v_mfma_f32_16x16x32_bf16 v[66:69], v[196:199], v[244:247], v[66:69]
	s_setprio 0
	s_add_i32 s59, s59, s37
	v_lshl_add_u64 v[200:201], s[24:25], 0, v[152:153]
	s_mov_b32 m0, s59
	ds_read_b128 v[206:209], v204 offset:16384
	ds_read_b128 v[210:213], v204 offset:17408
	ds_read_b128 v[214:217], v204 offset:18432
	ds_read_b128 v[218:221], v204 offset:19456
	ds_read_b128 v[222:225], v204 offset:20480
	ds_read_b128 v[226:229], v204 offset:21504
	ds_read_b128 v[230:233], v204 offset:22528
	ds_read_b128 v[244:247], v204 offset:23552
	global_load_lds_dwordx4 v[200:201], off
	s_add_i32 m0, s59, 0x2000
	s_add_u32 s60, s24, 0x40000
	v_lshl_add_u64 v[248:249], s[24:25], 0, v[156:157]
	s_addc_u32 s61, s25, 0
	s_add_i32 s59, s62, s37
	global_load_lds_dwordx4 v[248:249], off
	v_lshl_add_u64 v[250:251], s[60:61], 0, v[152:153]
	s_mov_b32 m0, s59
	v_lshl_add_u64 v[252:253], s[26:27], 0, v[154:155]
	global_load_lds_dwordx4 v[250:251], off
	v_lshl_add_u64 v[250:251], s[60:61], 0, v[156:157]
	s_add_i32 m0, s59, 0x2000
	s_nop 0
	global_load_lds_dwordx4 v[250:251], off
	v_lshl_add_u64 v[250:251], s[26:27], 0, v[150:151]
	s_mov_b32 m0, s38
	s_nop 0
	global_load_lds_dwordx4 v[250:251], off
	s_mov_b32 m0, s39
	s_nop 0
	global_load_lds_dwordx4 v[252:253], off
	s_waitcnt vmcnt(8)
	s_waitcnt lgkmcnt(0)
	s_barrier
; #define PG8_STAGE(bufoff, gbase, voff) do { _Pragma("unroll") for (int _i = 0; _i < 2; ++_i) \
;         __builtin_amdgcn_global_load_lds((const unsigned*)((const char*)(gbase) + (voff)[_i]), (PG8_LAS unsigned*)(lds + (bufoff) + ldsw + _i * 8192), 16, 0, 0); } while (0)
; #define PG8_LDA(dst, b, h) do { _Pragma("unroll") for (int m = 0; m < 4; ++m) _Pragma("unroll") for (int k = 0; k < 2; ++k) dst[m][k] = *(const PG8_LAS bf16x8*)(lds + PG8_SA(b, h) + aoff + m * 2048 + k * 1024); } while (0)
; #define PG8_LDB(dst, b, h) do { _Pragma("unroll") for (int n = 0; n < 2; ++n) _Pragma("unroll") for (int k = 0; k < 2; ++k) dst[n][k] = *(const PG8_LAS bf16x8*)(lds + PG8_SB(b, h) + boff + n * 2048 + k * 1024); } while (0)
; #define PG8_MMA(ai, bj, At, Bt) do { __builtin_amdgcn_s_setprio(1); _Pragma("unroll") for (int m = 0; m < 4; ++m) _Pragma("unroll") for (int n = 0; n < 2; ++n) _Pragma("unroll") for (int k = 0; k < 2; ++k) \
;         acc[ai][bj][m][n] = __builtin_amdgcn_mfma_f32_16x16x32_bf16(Bt[n][k], At[m][k], acc[ai][bj][m][n], 0, 0, 0); __builtin_amdgcn_s_setprio(0); } while (0)
; #define PG8_WAIT_V(n) asm volatile("s_waitcnt vmcnt(" #n ")" ::: "memory")
; #define PG8_WAIT_L(n) asm volatile("s_waitcnt lgkmcnt(" #n ")" ::: "memory")
; #define PG8_BAR __builtin_amdgcn_s_barrier()
; #define PG8_SCHED __builtin_amdgcn_sched_barrier(0)
; template <class Epi, class Sched, bool ALIGN_EPI = false, bool SP2 = false>
; __device__ __forceinline__ void gemm_phase(PG8_LAS unsigned char* lds, const Gemm g, const Sched& S, const Epi& E) {
;     ...
;             PG8_LDA(At, 0, 1); PG8_STAGE(PG8_SB(0, 0), b2, voffB); PG8_STAGE(PG8_SB(0, 1), b2 + hstep, voffB); PG8_STAGE(PG8_SA(0, 0), a2, voffA);
;             PG8_WAIT_V(8); PG8_WAIT_L(0); PG8_BAR; PG8_MMA(1, 0, At, B0); PG8_MMA(1, 1, At, B1); PG8_BAR; PG8_SCHED;
;             PG8_LDB(B0, 1, 0); PG8_LDB(B1, 1, 1); PG8_SCHED; PG8_LDA(At, 1, 0); PG8_STAGE(PG8_SA(0, 1), a2 + hstep, voffA);
;             PG8_WAIT_V(8); PG8_WAIT_L(0); PG8_BAR; PG8_MMA(0, 0, At, B0); PG8_MMA(0, 1, At, B1); PG8_BAR; PG8_SCHED;
;             PG8_LDA(At, 1, 1); PG8_STAGE(PG8_SB(1, 0), b3, voffB); PG8_STAGE(PG8_SB(1, 1), b3 + hstep, voffB); PG8_STAGE(PG8_SA(1, 0), a3, voffA);
	s_setprio 1
	s_waitcnt lgkmcnt(0)
	v_mfma_f32_16x16x32_bf16 v[62:65], v[130:133], v[206:209], v[62:65]
	v_mfma_f32_16x16x32_bf16 v[58:61], v[138:141], v[206:209], v[58:61]
	v_mfma_f32_16x16x32_bf16 v[46:49], v[130:133], v[214:217], v[46:49]
	v_mfma_f32_16x16x32_bf16 v[42:45], v[138:141], v[214:217], v[42:45]
	v_mfma_f32_16x16x32_bf16 v[30:33], v[130:133], v[222:225], v[30:33]
	v_mfma_f32_16x16x32_bf16 v[26:29], v[138:141], v[222:225], v[26:29]
	v_mfma_f32_16x16x32_bf16 v[14:17], v[130:133], v[230:233], v[14:17]
	v_mfma_f32_16x16x32_bf16 v[10:13], v[138:141], v[230:233], v[10:13]
	v_mfma_f32_16x16x32_bf16 v[62:65], v[134:137], v[210:213], v[62:65]
	v_mfma_f32_16x16x32_bf16 v[58:61], v[142:145], v[210:213], v[58:61]
	v_mfma_f32_16x16x32_bf16 v[46:49], v[134:137], v[218:221], v[46:49]
	v_mfma_f32_16x16x32_bf16 v[42:45], v[142:145], v[218:221], v[42:45]
	v_mfma_f32_16x16x32_bf16 v[30:33], v[134:137], v[226:229], v[30:33]
	v_mfma_f32_16x16x32_bf16 v[26:29], v[142:145], v[226:229], v[26:29]
	v_mfma_f32_16x16x32_bf16 v[14:17], v[134:137], v[244:247], v[14:17]
	v_mfma_f32_16x16x32_bf16 v[10:13], v[142:145], v[244:247], v[10:13]
	s_setprio 0
	s_setprio 1
	v_mfma_f32_16x16x32_bf16 v[54:57], v[146:149], v[206:209], v[54:57]
	v_mfma_f32_16x16x32_bf16 v[50:53], v[192:195], v[206:209], v[50:53]
	v_mfma_f32_16x16x32_bf16 v[38:41], v[146:149], v[214:217], v[38:41]
	v_mfma_f32_16x16x32_bf16 v[34:37], v[192:195], v[214:217], v[34:37]
	v_mfma_f32_16x16x32_bf16 v[22:25], v[146:149], v[222:225], v[22:25]
	v_mfma_f32_16x16x32_bf16 v[18:21], v[192:195], v[222:225], v[18:21]
	v_mfma_f32_16x16x32_bf16 v[6:9], v[146:149], v[230:233], v[6:9]
	v_mfma_f32_16x16x32_bf16 v[2:5], v[192:195], v[230:233], v[2:5]
	v_mfma_f32_16x16x32_bf16 v[54:57], v[162:165], v[210:213], v[54:57]
	v_mfma_f32_16x16x32_bf16 v[50:53], v[196:199], v[210:213], v[50:53]
	v_mfma_f32_16x16x32_bf16 v[38:41], v[162:165], v[218:221], v[38:41]
	v_mfma_f32_16x16x32_bf16 v[34:37], v[196:199], v[218:221], v[34:37]
	v_mfma_f32_16x16x32_bf16 v[22:25], v[162:165], v[226:229], v[22:25]
	v_mfma_f32_16x16x32_bf16 v[18:21], v[196:199], v[226:229], v[18:21]
	v_mfma_f32_16x16x32_bf16 v[6:9], v[162:165], v[244:247], v[6:9]
	s_setprio 3
	s_barrier
	v_mfma_f32_16x16x32_bf16 v[2:5], v[196:199], v[244:247], v[2:5]
	s_setprio 0
	s_add_i32 s59, 0, 0x18000
	v_add_u32_e32 v0, s59, v202
	s_add_i32 s60, 0, 0x1c000
	ds_read_b128 v[130:133], v0
	ds_read_b128 v[134:137], v0 offset:1024
	ds_read_b128 v[138:141], v0 offset:2048
	ds_read_b128 v[142:145], v0 offset:3072
	v_add_u32_e32 v0, s60, v202
	ds_read_b128 v[146:149], v0
	ds_read_b128 v[162:165], v0 offset:1024
	ds_read_b128 v[192:195], v0 offset:2048
	ds_read_b128 v[196:199], v0 offset:3072
	s_add_u32 s26, s26, 0x40000
	s_addc_u32 s27, s27, 0
	s_mov_b32 m0, s40
	v_lshl_add_u64 v[236:237], s[26:27], 0, v[150:151]
	ds_read_b128 v[206:209], v204 offset:32768
	ds_read_b128 v[210:213], v204 offset:33792
	ds_read_b128 v[214:217], v204 offset:34816
	ds_read_b128 v[218:221], v204 offset:35840
	ds_read_b128 v[222:225], v204 offset:36864
	ds_read_b128 v[226:229], v204 offset:37888
	ds_read_b128 v[230:233], v204 offset:38912
	ds_read_b128 v[244:247], v204 offset:39936
	global_load_lds_dwordx4 v[236:237], off
	v_lshl_add_u64 v[236:237], s[26:27], 0, v[154:155]
	s_mov_b32 m0, s41
	s_nop 0
	global_load_lds_dwordx4 v[236:237], off
	s_waitcnt vmcnt(8)
	s_waitcnt lgkmcnt(0)
	s_barrier
	s_setprio 1
	s_waitcnt lgkmcnt(0)
	v_mfma_f32_16x16x32_bf16 v[126:129], v[130:133], v[206:209], v[126:129]
	v_mfma_f32_16x16x32_bf16 v[122:125], v[138:141], v[206:209], v[122:125]
	v_mfma_f32_16x16x32_bf16 v[110:113], v[130:133], v[214:217], v[110:113]
	v_mfma_f32_16x16x32_bf16 v[106:109], v[138:141], v[214:217], v[106:109]
	v_mfma_f32_16x16x32_bf16 v[94:97], v[130:133], v[222:225], v[94:97]
	v_mfma_f32_16x16x32_bf16 v[90:93], v[138:141], v[222:225], v[90:93]
	v_mfma_f32_16x16x32_bf16 v[78:81], v[130:133], v[230:233], v[78:81]
	v_mfma_f32_16x16x32_bf16 v[74:77], v[138:141], v[230:233], v[74:77]
	v_mfma_f32_16x16x32_bf16 v[126:129], v[134:137], v[210:213], v[126:129]
	v_mfma_f32_16x16x32_bf16 v[122:125], v[142:145], v[210:213], v[122:125]
	v_mfma_f32_16x16x32_bf16 v[110:113], v[134:137], v[218:221], v[110:113]
	v_mfma_f32_16x16x32_bf16 v[106:109], v[142:145], v[218:221], v[106:109]
	v_mfma_f32_16x16x32_bf16 v[94:97], v[134:137], v[226:229], v[94:97]
	v_mfma_f32_16x16x32_bf16 v[90:93], v[142:145], v[226:229], v[90:93]
	v_mfma_f32_16x16x32_bf16 v[78:81], v[134:137], v[244:247], v[78:81]
	v_mfma_f32_16x16x32_bf16 v[74:77], v[142:145], v[244:247], v[74:77]
	s_setprio 0
	s_setprio 1
	v_mfma_f32_16x16x32_bf16 v[118:121], v[146:149], v[206:209], v[118:121]
	v_mfma_f32_16x16x32_bf16 v[114:117], v[192:195], v[206:209], v[114:117]
	v_mfma_f32_16x16x32_bf16 v[102:105], v[146:149], v[214:217], v[102:105]
	v_mfma_f32_16x16x32_bf16 v[98:101], v[192:195], v[214:217], v[98:101]
	v_mfma_f32_16x16x32_bf16 v[86:89], v[146:149], v[222:225], v[86:89]
	v_mfma_f32_16x16x32_bf16 v[82:85], v[192:195], v[222:225], v[82:85]
	v_mfma_f32_16x16x32_bf16 v[70:73], v[146:149], v[230:233], v[70:73]
	v_mfma_f32_16x16x32_bf16 v[66:69], v[192:195], v[230:233], v[66:69]
	v_mfma_f32_16x16x32_bf16 v[118:121], v[162:165], v[210:213], v[118:121]
	v_mfma_f32_16x16x32_bf16 v[114:117], v[196:199], v[210:213], v[114:117]
	v_mfma_f32_16x16x32_bf16 v[102:105], v[162:165], v[218:221], v[102:105]
	v_mfma_f32_16x16x32_bf16 v[98:101], v[196:199], v[218:221], v[98:101]
	v_mfma_f32_16x16x32_bf16 v[86:89], v[162:165], v[226:229], v[86:89]
	v_mfma_f32_16x16x32_bf16 v[82:85], v[196:199], v[226:229], v[82:85]
	v_mfma_f32_16x16x32_bf16 v[70:73], v[162:165], v[244:247], v[70:73]
	s_setprio 3
	s_barrier
; #define PG8_STAGE(bufoff, gbase, voff) do { _Pragma("unroll") for (int _i = 0; _i < 2; ++_i) \
;         __builtin_amdgcn_global_load_lds((const unsigned*)((const char*)(gbase) + (voff)[_i]), (PG8_LAS unsigned*)(lds + (bufoff) + ldsw + _i * 8192), 16, 0, 0); } while (0)
; #define PG8_LDA(dst, b, h) do { _Pragma("unroll") for (int m = 0; m < 4; ++m) _Pragma("unroll") for (int k = 0; k < 2; ++k) dst[m][k] = *(const PG8_LAS bf16x8*)(lds + PG8_SA(b, h) + aoff + m * 2048 + k * 1024); } while (0)
; #define PG8_MMA(ai, bj, At, Bt) do { __builtin_amdgcn_s_setprio(1); _Pragma("unroll") for (int m = 0; m < 4; ++m) _Pragma("unroll") for (int n = 0; n < 2; ++n) _Pragma("unroll") for (int k = 0; k < 2; ++k) \
;         acc[ai][bj][m][n] = __builtin_amdgcn_mfma_f32_16x16x32_bf16(Bt[n][k], At[m][k], acc[ai][bj][m][n], 0, 0, 0); __builtin_amdgcn_s_setprio(0); } while (0)
; #define PG8_WAIT_V(n) asm volatile("s_waitcnt vmcnt(" #n ")" ::: "memory")
; #define PG8_WAIT_L(n) asm volatile("s_waitcnt lgkmcnt(" #n ")" ::: "memory")
; #define PG8_BAR __builtin_amdgcn_s_barrier()
; #define PG8_SCHED __builtin_amdgcn_sched_barrier(0)
;     __device__ __forceinline__ void operator()(const f32x4 (&acc)[2][2][4][2], const Unit& u, int wr, int wc, int fr, int fq) const {
;         if (u.pn < 18) { q(acc, u, wr, wc, fr, fq); return; }
; template <class Epi, class Sched, bool ALIGN_EPI = false, bool SP2 = false>
; __device__ __forceinline__ void gemm_phase(PG8_LAS unsigned char* lds, const Gemm g, const Sched& S, const Epi& E) {
;     ...
;             PG8_LDA(At, 1, 1); PG8_STAGE(PG8_SB(1, 0), b3, voffB); PG8_STAGE(PG8_SB(1, 1), b3 + hstep, voffB); PG8_STAGE(PG8_SA(1, 0), a3, voffA);
;             PG8_WAIT_V(8); PG8_WAIT_L(0); PG8_BAR; PG8_MMA(1, 0, At, B0); PG8_MMA(1, 1, At, B1); PG8_BAR; PG8_SCHED;
	v_mfma_f32_16x16x32_bf16 v[66:69], v[196:199], v[244:247], v[66:69]
	s_setprio 0
	s_add_i32 s26, s59, s37
	v_lshl_add_u64 v[200:201], v[200:201], 0, vcc
	s_mov_b32 m0, s26
	ds_read_b128 v[206:209], v204 offset:49152
	ds_read_b128 v[210:213], v204 offset:50176
	ds_read_b128 v[214:217], v204 offset:51200
	ds_read_b128 v[218:221], v204 offset:52224
	ds_read_b128 v[222:225], v204 offset:53248
	ds_read_b128 v[226:229], v204 offset:54272
	ds_read_b128 v[230:233], v204 offset:55296
	ds_read_b128 v[244:247], v204 offset:56320
	global_load_lds_dwordx4 v[200:201], off
	s_add_i32 m0, s26, 0x2000
	s_add_u32 s24, s24, 0x40080
	v_lshl_add_u64 v[200:201], v[248:249], 0, vcc
	s_addc_u32 s25, s25, 0
	s_add_i32 s26, s60, s37
	global_load_lds_dwordx4 v[200:201], off
	v_lshl_add_u64 v[200:201], s[24:25], 0, v[152:153]
	s_mov_b32 m0, s26
	s_nop 0
	global_load_lds_dwordx4 v[200:201], off
	v_lshl_add_u64 v[200:201], s[24:25], 0, v[156:157]
	s_add_i32 m0, s26, 0x2000
	s_nop 0
	global_load_lds_dwordx4 v[200:201], off
	v_lshl_add_u64 v[200:201], v[250:251], 0, vcc
	s_mov_b32 m0, s51
	s_nop 0
	global_load_lds_dwordx4 v[200:201], off
	v_lshl_add_u64 v[200:201], v[252:253], 0, vcc
	s_mov_b32 m0, s52
	s_nop 0
	global_load_lds_dwordx4 v[200:201], off
	s_waitcnt vmcnt(8)
	s_waitcnt lgkmcnt(0)
	s_barrier
	s_setprio 1
	s_waitcnt lgkmcnt(0)
	v_mfma_f32_16x16x32_bf16 v[62:65], v[130:133], v[206:209], v[62:65]
	v_mfma_f32_16x16x32_bf16 v[58:61], v[138:141], v[206:209], v[58:61]
	v_mfma_f32_16x16x32_bf16 v[46:49], v[130:133], v[214:217], v[46:49]
	v_mfma_f32_16x16x32_bf16 v[42:45], v[138:141], v[214:217], v[42:45]
	v_mfma_f32_16x16x32_bf16 v[30:33], v[130:133], v[222:225], v[30:33]
	v_mfma_f32_16x16x32_bf16 v[26:29], v[138:141], v[222:225], v[26:29]
	v_mfma_f32_16x16x32_bf16 v[14:17], v[130:133], v[230:233], v[14:17]
	v_mfma_f32_16x16x32_bf16 v[10:13], v[138:141], v[230:233], v[10:13]
	v_mfma_f32_16x16x32_bf16 v[62:65], v[134:137], v[210:213], v[62:65]
	v_mfma_f32_16x16x32_bf16 v[58:61], v[142:145], v[210:213], v[58:61]
	v_mfma_f32_16x16x32_bf16 v[46:49], v[134:137], v[218:221], v[46:49]
	v_mfma_f32_16x16x32_bf16 v[42:45], v[142:145], v[218:221], v[42:45]
	v_mfma_f32_16x16x32_bf16 v[30:33], v[134:137], v[226:229], v[30:33]
	v_mfma_f32_16x16x32_bf16 v[26:29], v[142:145], v[226:229], v[26:29]
	v_mfma_f32_16x16x32_bf16 v[14:17], v[134:137], v[244:247], v[14:17]
	v_mfma_f32_16x16x32_bf16 v[10:13], v[142:145], v[244:247], v[10:13]
	s_setprio 0
	s_setprio 1
	v_mfma_f32_16x16x32_bf16 v[54:57], v[146:149], v[206:209], v[54:57]
	v_mfma_f32_16x16x32_bf16 v[50:53], v[192:195], v[206:209], v[50:53]
	v_mfma_f32_16x16x32_bf16 v[38:41], v[146:149], v[214:217], v[38:41]
	v_mfma_f32_16x16x32_bf16 v[34:37], v[192:195], v[214:217], v[34:37]
	v_mfma_f32_16x16x32_bf16 v[22:25], v[146:149], v[222:225], v[22:25]
	v_mfma_f32_16x16x32_bf16 v[18:21], v[192:195], v[222:225], v[18:21]
	v_mfma_f32_16x16x32_bf16 v[6:9], v[146:149], v[230:233], v[6:9]
	v_mfma_f32_16x16x32_bf16 v[2:5], v[192:195], v[230:233], v[2:5]
	v_mfma_f32_16x16x32_bf16 v[54:57], v[162:165], v[210:213], v[54:57]
	v_mfma_f32_16x16x32_bf16 v[50:53], v[196:199], v[210:213], v[50:53]
	v_mfma_f32_16x16x32_bf16 v[38:41], v[162:165], v[218:221], v[38:41]
	v_mfma_f32_16x16x32_bf16 v[34:37], v[196:199], v[218:221], v[34:37]
	v_mfma_f32_16x16x32_bf16 v[22:25], v[162:165], v[226:229], v[22:25]
	v_mfma_f32_16x16x32_bf16 v[18:21], v[196:199], v[226:229], v[18:21]
	v_mfma_f32_16x16x32_bf16 v[6:9], v[162:165], v[244:247], v[6:9]
	s_setprio 3
	s_barrier
	v_mfma_f32_16x16x32_bf16 v[2:5], v[196:199], v[244:247], v[2:5]
	s_setprio 0
	s_add_i32 s58, s58, 2
	s_add_u32 s56, s56, 0x100
	s_addc_u32 s57, s57, 0
	s_add_u32 s22, s22, 0x100
	s_addc_u32 s23, s23, 0
	s_cmp_gt_u32 s58, 13
	s_cbranch_scc0 .LBB0_166
	s_and_b64 vcc, exec, s[4:5]
	s_cbranch_vccnz .LBB0_170
	s_mov_b64 s[22:23], -1
	s_cmp_gt_i32 s10, 17
	v_lshl_add_u32 v162, s20, 8, v182
	s_cbranch_scc1 .LBB0_171

; #define PG8_STAGE(bufoff, gbase, voff) do { _Pragma("unroll") for (int _i = 0; _i < 2; ++_i) \
;         __builtin_amdgcn_global_load_lds((const unsigned*)((const char*)(gbase) + (voff)[_i]), (PG8_LAS unsigned*)(lds + (bufoff) + ldsw + _i * 8192), 16, 0, 0); } while (0)
; #define PG8_LDA(dst, b, h) do { _Pragma("unroll") for (int m = 0; m < 4; ++m) _Pragma("unroll") for (int k = 0; k < 2; ++k) dst[m][k] = *(const PG8_LAS bf16x8*)(lds + PG8_SA(b, h) + aoff + m * 2048 + k * 1024); } while (0)
; #define PG8_LDB(dst, b, h) do { _Pragma("unroll") for (int n = 0; n < 2; ++n) _Pragma("unroll") for (int k = 0; k < 2; ++k) dst[n][k] = *(const PG8_LAS bf16x8*)(lds + PG8_SB(b, h) + boff + n * 2048 + k * 1024); } while (0)
; #define PG8_MMA(ai, bj, At, Bt) do { __builtin_amdgcn_s_setprio(1); _Pragma("unroll") for (int m = 0; m < 4; ++m) _Pragma("unroll") for (int n = 0; n < 2; ++n) _Pragma("unroll") for (int k = 0; k < 2; ++k) \
;         acc[ai][bj][m][n] = __builtin_amdgcn_mfma_f32_16x16x32_bf16(Bt[n][k], At[m][k], acc[ai][bj][m][n], 0, 0, 0); __builtin_amdgcn_s_setprio(0); } while (0)
; #define PG8_WAIT_V(n) asm volatile("s_waitcnt vmcnt(" #n ")" ::: "memory")
; #define PG8_BAR __builtin_amdgcn_s_barrier()
; template <class Epi, class Sched, bool ALIGN_EPI = false, bool SP2 = false>
; __device__ __forceinline__ void gemm_phase(PG8_LAS unsigned char* lds, const Gemm g, const Sched& S, const Epi& E) {
;     ...
;         for (int t = 0; t < nt; t += 2) {
;             const bool last = (t == nt - 2);
;             const char* a1 = cA + (size_t)(t + 1) * kstep;
;             const char* a2 = last ? nA : cA + (size_t)(t + 2) * kstep; const char* b2 = last ? nB : cB + (size_t)(t + 2) * kstep;
;             const char* a3 = a2 + kstep; const char* b3 = b2 + kstep;
;             if (last && has_next) S.a_ready(nxt);
;             if constexpr (SP2) {
;             PG8_LDB(B0, 0, 0); PG8_LDB(B1, 0, 1); PG8_SCHED; PG8_LDA(At, 0, 0); PG8_STAGE(PG8_SA(1, 1), a1 + hstep, voffA);
;             PG8_WAIT_V(8); PG8_WAIT_L(0); PG8_BAR; PG8_MMA(0, 0, At, B0); PG8_MMA(0, 1, At, B1); PG8_BAR; PG8_SCHED;
;             PG8_LDA(At, 0, 1); PG8_STAGE(PG8_SB(0, 0), b2, voffB); PG8_STAGE(PG8_SB(0, 1), b2 + hstep, voffB); PG8_STAGE(PG8_SA(0, 0), a2, voffA);
;             PG8_WAIT_V(8); PG8_WAIT_L(0); PG8_BAR; PG8_MMA(1, 0, At, B0); PG8_MMA(1, 1, At, B1); PG8_BAR; PG8_SCHED;
.LBB0_514:
	s_add_u32 s20, s6, 0xfffe0080
	s_addc_u32 s21, s7, -1
	s_add_i32 s50, 0, 0x10000
	s_cmp_eq_u32 s49, 4
	s_cselect_b32 s23, s11, s21
	s_cselect_b32 s22, s25, s20
	v_add_u32_e32 v0, s50, v159
	s_cselect_b32 s21, s13, s48
	s_cselect_b32 s20, s46, s47
	s_add_i32 s52, 0, 0x14000
	ds_read_b128 v[144:147], v0
	ds_read_b128 v[148:151], v0 offset:1024
	ds_read_b128 v[152:155], v0 offset:2048
	ds_read_b128 v[162:165], v0 offset:3072
	v_add_u32_e32 v0, s52, v159
	ds_read_b128 v[192:195], v0
	ds_read_b128 v[196:199], v0 offset:1024
	ds_read_b128 v[200:203], v0 offset:2048
	ds_read_b128 v[204:207], v0 offset:3072
	v_lshl_add_u64 v[2:3], s[6:7], 0, v[142:143]
	s_add_i32 m0, s9, 0xc000
	ds_read_b128 v[208:211], v161
	ds_read_b128 v[212:215], v161 offset:1024
	ds_read_b128 v[216:219], v161 offset:2048
	ds_read_b128 v[220:223], v161 offset:3072
	ds_read_b128 v[224:227], v161 offset:4096
	ds_read_b128 v[228:231], v161 offset:5120
	ds_read_b128 v[244:247], v161 offset:6144
	ds_read_b128 v[248:251], v161 offset:7168
	global_load_lds_dwordx4 v[2:3], off
	v_lshl_add_u64 v[2:3], s[6:7], 0, v[140:141]
	s_add_i32 m0, s9, 0xe000
	s_nop 0
	global_load_lds_dwordx4 v[2:3], off
	s_waitcnt vmcnt(8)
	s_waitcnt lgkmcnt(0)
	s_barrier
	s_setprio 1
	s_waitcnt lgkmcnt(0)
	v_mfma_f32_16x16x32_bf16 v[128:131], v[144:147], v[208:211], v[128:131]
	v_mfma_f32_16x16x32_bf16 v[124:127], v[152:155], v[208:211], v[124:127]
	v_mfma_f32_16x16x32_bf16 v[120:123], v[144:147], v[216:219], v[120:123]
	v_mfma_f32_16x16x32_bf16 v[116:119], v[152:155], v[216:219], v[116:119]
	v_mfma_f32_16x16x32_bf16 v[112:115], v[144:147], v[224:227], v[112:115]
	v_mfma_f32_16x16x32_bf16 v[108:111], v[152:155], v[224:227], v[108:111]
	v_mfma_f32_16x16x32_bf16 v[104:107], v[144:147], v[244:247], v[104:107]
	v_mfma_f32_16x16x32_bf16 v[100:103], v[152:155], v[244:247], v[100:103]
	v_mfma_f32_16x16x32_bf16 v[128:131], v[148:151], v[212:215], v[128:131]
	v_mfma_f32_16x16x32_bf16 v[124:127], v[162:165], v[212:215], v[124:127]
	v_mfma_f32_16x16x32_bf16 v[120:123], v[148:151], v[220:223], v[120:123]
	v_mfma_f32_16x16x32_bf16 v[116:119], v[162:165], v[220:223], v[116:119]
	v_mfma_f32_16x16x32_bf16 v[112:115], v[148:151], v[228:231], v[112:115]
	v_mfma_f32_16x16x32_bf16 v[108:111], v[162:165], v[228:231], v[108:111]
	v_mfma_f32_16x16x32_bf16 v[104:107], v[148:151], v[248:251], v[104:107]
	v_mfma_f32_16x16x32_bf16 v[100:103], v[162:165], v[248:251], v[100:103]
	s_setprio 0
	s_setprio 1
	v_mfma_f32_16x16x32_bf16 v[96:99], v[192:195], v[208:211], v[96:99]
	v_mfma_f32_16x16x32_bf16 v[92:95], v[200:203], v[208:211], v[92:95]
	v_mfma_f32_16x16x32_bf16 v[88:91], v[192:195], v[216:219], v[88:91]
	v_mfma_f32_16x16x32_bf16 v[84:87], v[200:203], v[216:219], v[84:87]
	v_mfma_f32_16x16x32_bf16 v[80:83], v[192:195], v[224:227], v[80:83]
	v_mfma_f32_16x16x32_bf16 v[76:79], v[200:203], v[224:227], v[76:79]
	v_mfma_f32_16x16x32_bf16 v[72:75], v[192:195], v[244:247], v[72:75]
	v_mfma_f32_16x16x32_bf16 v[68:71], v[200:203], v[244:247], v[68:71]
	v_mfma_f32_16x16x32_bf16 v[96:99], v[196:199], v[212:215], v[96:99]
	v_mfma_f32_16x16x32_bf16 v[92:95], v[204:207], v[212:215], v[92:95]
	v_mfma_f32_16x16x32_bf16 v[88:91], v[196:199], v[220:223], v[88:91]
	v_mfma_f32_16x16x32_bf16 v[84:87], v[204:207], v[220:223], v[84:87]
	v_mfma_f32_16x16x32_bf16 v[80:83], v[196:199], v[228:231], v[80:83]
	v_mfma_f32_16x16x32_bf16 v[76:79], v[204:207], v[228:231], v[76:79]
	v_mfma_f32_16x16x32_bf16 v[72:75], v[196:199], v[248:251], v[72:75]
	s_setprio 3
	s_barrier
	v_mfma_f32_16x16x32_bf16 v[68:71], v[204:207], v[248:251], v[68:71]
	s_setprio 0
	s_add_i32 s50, s50, s30
	v_lshl_add_u64 v[156:157], s[20:21], 0, v[136:137]
	s_mov_b32 m0, s50
	ds_read_b128 v[208:211], v161 offset:16384
	ds_read_b128 v[212:215], v161 offset:17408
	ds_read_b128 v[216:219], v161 offset:18432
	ds_read_b128 v[220:223], v161 offset:19456
	ds_read_b128 v[224:227], v161 offset:20480
	ds_read_b128 v[228:231], v161 offset:21504
	ds_read_b128 v[244:247], v161 offset:22528
	ds_read_b128 v[248:251], v161 offset:23552
	global_load_lds_dwordx4 v[156:157], off
	s_add_i32 m0, s50, 0x2000
	s_add_u32 s50, s20, 0x20000
	v_lshl_add_u64 v[232:233], s[20:21], 0, v[132:133]
	s_addc_u32 s51, s21, 0
	s_add_i32 s52, s52, s30
	global_load_lds_dwordx4 v[232:233], off
	v_lshl_add_u64 v[2:3], s[50:51], 0, v[136:137]
	s_mov_b32 m0, s52
	v_lshl_add_u64 v[236:237], s[22:23], 0, v[138:139]
	global_load_lds_dwordx4 v[2:3], off
	v_lshl_add_u64 v[2:3], s[50:51], 0, v[132:133]
	s_add_i32 m0, s52, 0x2000
	v_lshl_add_u64 v[252:253], s[22:23], 0, v[134:135]
	global_load_lds_dwordx4 v[2:3], off
	s_mov_b32 m0, s9
	s_nop 0
	global_load_lds_dwordx4 v[236:237], off
	s_mov_b32 m0, s36
	s_nop 0
	global_load_lds_dwordx4 v[252:253], off
	s_waitcnt vmcnt(8)
	s_waitcnt lgkmcnt(0)
	s_barrier
; #define PG8_STAGE(bufoff, gbase, voff) do { _Pragma("unroll") for (int _i = 0; _i < 2; ++_i) \
;         __builtin_amdgcn_global_load_lds((const unsigned*)((const char*)(gbase) + (voff)[_i]), (PG8_LAS unsigned*)(lds + (bufoff) + ldsw + _i * 8192), 16, 0, 0); } while (0)
; #define PG8_LDA(dst, b, h) do { _Pragma("unroll") for (int m = 0; m < 4; ++m) _Pragma("unroll") for (int k = 0; k < 2; ++k) dst[m][k] = *(const PG8_LAS bf16x8*)(lds + PG8_SA(b, h) + aoff + m * 2048 + k * 1024); } while (0)
; #define PG8_LDB(dst, b, h) do { _Pragma("unroll") for (int n = 0; n < 2; ++n) _Pragma("unroll") for (int k = 0; k < 2; ++k) dst[n][k] = *(const PG8_LAS bf16x8*)(lds + PG8_SB(b, h) + boff + n * 2048 + k * 1024); } while (0)
; #define PG8_MMA(ai, bj, At, Bt) do { __builtin_amdgcn_s_setprio(1); _Pragma("unroll") for (int m = 0; m < 4; ++m) _Pragma("unroll") for (int n = 0; n < 2; ++n) _Pragma("unroll") for (int k = 0; k < 2; ++k) \
;         acc[ai][bj][m][n] = __builtin_amdgcn_mfma_f32_16x16x32_bf16(Bt[n][k], At[m][k], acc[ai][bj][m][n], 0, 0, 0); __builtin_amdgcn_s_setprio(0); } while (0)
; #define PG8_WAIT_V(n) asm volatile("s_waitcnt vmcnt(" #n ")" ::: "memory")
; #define PG8_WAIT_L(n) asm volatile("s_waitcnt lgkmcnt(" #n ")" ::: "memory")
; #define PG8_BAR __builtin_amdgcn_s_barrier()
; #define PG8_SCHED __builtin_amdgcn_sched_barrier(0)
; template <class Epi, class Sched, bool ALIGN_EPI = false, bool SP2 = false>
; __device__ __forceinline__ void gemm_phase(PG8_LAS unsigned char* lds, const Gemm g, const Sched& S, const Epi& E) {
;     ...
;             PG8_LDA(At, 0, 1); PG8_STAGE(PG8_SB(0, 0), b2, voffB); PG8_STAGE(PG8_SB(0, 1), b2 + hstep, voffB); PG8_STAGE(PG8_SA(0, 0), a2, voffA);
;             PG8_WAIT_V(8); PG8_WAIT_L(0); PG8_BAR; PG8_MMA(1, 0, At, B0); PG8_MMA(1, 1, At, B1); PG8_BAR; PG8_SCHED;
;             PG8_LDB(B0, 1, 0); PG8_LDB(B1, 1, 1); PG8_SCHED; PG8_LDA(At, 1, 0); PG8_STAGE(PG8_SA(0, 1), a2 + hstep, voffA);
;             PG8_WAIT_V(8); PG8_WAIT_L(0); PG8_BAR; PG8_MMA(0, 0, At, B0); PG8_MMA(0, 1, At, B1); PG8_BAR; PG8_SCHED;
;             PG8_LDA(At, 1, 1); PG8_STAGE(PG8_SB(1, 0), b3, voffB); PG8_STAGE(PG8_SB(1, 1), b3 + hstep, voffB); PG8_STAGE(PG8_SA(1, 0), a3, voffA);
	s_setprio 1
	s_waitcnt lgkmcnt(0)
	v_mfma_f32_16x16x32_bf16 v[64:67], v[144:147], v[208:211], v[64:67]
	v_mfma_f32_16x16x32_bf16 v[60:63], v[152:155], v[208:211], v[60:63]
	v_mfma_f32_16x16x32_bf16 v[56:59], v[144:147], v[216:219], v[56:59]
	v_mfma_f32_16x16x32_bf16 v[52:55], v[152:155], v[216:219], v[52:55]
	v_mfma_f32_16x16x32_bf16 v[48:51], v[144:147], v[224:227], v[48:51]
	v_mfma_f32_16x16x32_bf16 v[44:47], v[152:155], v[224:227], v[44:47]
	v_mfma_f32_16x16x32_bf16 v[40:43], v[144:147], v[244:247], v[40:43]
	v_mfma_f32_16x16x32_bf16 v[36:39], v[152:155], v[244:247], v[36:39]
	v_mfma_f32_16x16x32_bf16 v[64:67], v[148:151], v[212:215], v[64:67]
	v_mfma_f32_16x16x32_bf16 v[60:63], v[162:165], v[212:215], v[60:63]
	v_mfma_f32_16x16x32_bf16 v[56:59], v[148:151], v[220:223], v[56:59]
	v_mfma_f32_16x16x32_bf16 v[52:55], v[162:165], v[220:223], v[52:55]
	v_mfma_f32_16x16x32_bf16 v[48:51], v[148:151], v[228:231], v[48:51]
	v_mfma_f32_16x16x32_bf16 v[44:47], v[162:165], v[228:231], v[44:47]
	v_mfma_f32_16x16x32_bf16 v[40:43], v[148:151], v[248:251], v[40:43]
	v_mfma_f32_16x16x32_bf16 v[36:39], v[162:165], v[248:251], v[36:39]
	s_setprio 0
	s_setprio 1
	v_mfma_f32_16x16x32_bf16 v[32:35], v[192:195], v[208:211], v[32:35]
	v_mfma_f32_16x16x32_bf16 v[28:31], v[200:203], v[208:211], v[28:31]
	v_mfma_f32_16x16x32_bf16 v[24:27], v[192:195], v[216:219], v[24:27]
	v_mfma_f32_16x16x32_bf16 v[20:23], v[200:203], v[216:219], v[20:23]
	v_mfma_f32_16x16x32_bf16 v[16:19], v[192:195], v[224:227], v[16:19]
	v_mfma_f32_16x16x32_bf16 v[12:15], v[200:203], v[224:227], v[12:15]
	v_mfma_f32_16x16x32_bf16 v[8:11], v[192:195], v[244:247], v[8:11]
	v_mfma_f32_16x16x32_bf16 v[2:5], v[200:203], v[244:247], v[4:7]
	v_mfma_f32_16x16x32_bf16 v[32:35], v[196:199], v[212:215], v[32:35]
	v_mfma_f32_16x16x32_bf16 v[28:31], v[204:207], v[212:215], v[28:31]
	v_mfma_f32_16x16x32_bf16 v[24:27], v[196:199], v[220:223], v[24:27]
	v_mfma_f32_16x16x32_bf16 v[20:23], v[204:207], v[220:223], v[20:23]
	v_mfma_f32_16x16x32_bf16 v[16:19], v[196:199], v[228:231], v[16:19]
	v_mfma_f32_16x16x32_bf16 v[12:15], v[204:207], v[228:231], v[12:15]
	v_mfma_f32_16x16x32_bf16 v[8:11], v[196:199], v[248:251], v[8:11]
	s_setprio 3
	s_barrier
	v_mfma_f32_16x16x32_bf16 v[2:5], v[204:207], v[248:251], v[2:5]
	s_setprio 0
	s_add_i32 s50, 0, 0x18000
	v_add_u32_e32 v0, s50, v159
	s_add_i32 s51, 0, 0x1c000
	ds_read_b128 v[144:147], v0
	ds_read_b128 v[148:151], v0 offset:1024
	ds_read_b128 v[152:155], v0 offset:2048
	ds_read_b128 v[162:165], v0 offset:3072
	v_add_u32_e32 v0, s51, v159
	ds_read_b128 v[192:195], v0
	ds_read_b128 v[196:199], v0 offset:1024
	ds_read_b128 v[200:203], v0 offset:2048
	ds_read_b128 v[204:207], v0 offset:3072
	s_add_u32 s22, s22, 0x20000
	s_addc_u32 s23, s23, 0
	s_mov_b32 m0, s37
	v_lshl_add_u64 v[6:7], s[22:23], 0, v[138:139]
	ds_read_b128 v[208:211], v161 offset:32768
	ds_read_b128 v[212:215], v161 offset:33792
	ds_read_b128 v[216:219], v161 offset:34816
	ds_read_b128 v[220:223], v161 offset:35840
	ds_read_b128 v[224:227], v161 offset:36864
	ds_read_b128 v[228:231], v161 offset:37888
	ds_read_b128 v[244:247], v161 offset:38912
	ds_read_b128 v[248:251], v161 offset:39936
	global_load_lds_dwordx4 v[6:7], off
	v_lshl_add_u64 v[6:7], s[22:23], 0, v[134:135]
	s_mov_b32 m0, s38
	s_nop 0
	global_load_lds_dwordx4 v[6:7], off
	s_waitcnt vmcnt(8)
	s_waitcnt lgkmcnt(0)
	s_barrier
	s_setprio 1
	s_waitcnt lgkmcnt(0)
	v_mfma_f32_16x16x32_bf16 v[128:131], v[144:147], v[208:211], v[128:131]
	v_mfma_f32_16x16x32_bf16 v[124:127], v[152:155], v[208:211], v[124:127]
	v_mfma_f32_16x16x32_bf16 v[120:123], v[144:147], v[216:219], v[120:123]
	v_mfma_f32_16x16x32_bf16 v[116:119], v[152:155], v[216:219], v[116:119]
	v_mfma_f32_16x16x32_bf16 v[112:115], v[144:147], v[224:227], v[112:115]
	v_mfma_f32_16x16x32_bf16 v[108:111], v[152:155], v[224:227], v[108:111]
	v_mfma_f32_16x16x32_bf16 v[104:107], v[144:147], v[244:247], v[104:107]
	v_mfma_f32_16x16x32_bf16 v[100:103], v[152:155], v[244:247], v[100:103]
	v_mfma_f32_16x16x32_bf16 v[128:131], v[148:151], v[212:215], v[128:131]
	v_mfma_f32_16x16x32_bf16 v[124:127], v[162:165], v[212:215], v[124:127]
	v_mfma_f32_16x16x32_bf16 v[120:123], v[148:151], v[220:223], v[120:123]
	v_mfma_f32_16x16x32_bf16 v[116:119], v[162:165], v[220:223], v[116:119]
	v_mfma_f32_16x16x32_bf16 v[112:115], v[148:151], v[228:231], v[112:115]
	v_mfma_f32_16x16x32_bf16 v[108:111], v[162:165], v[228:231], v[108:111]
	v_mfma_f32_16x16x32_bf16 v[104:107], v[148:151], v[248:251], v[104:107]
	v_mfma_f32_16x16x32_bf16 v[100:103], v[162:165], v[248:251], v[100:103]
	s_setprio 0
	s_setprio 1
	v_mfma_f32_16x16x32_bf16 v[96:99], v[192:195], v[208:211], v[96:99]
	v_mfma_f32_16x16x32_bf16 v[92:95], v[200:203], v[208:211], v[92:95]
	v_mfma_f32_16x16x32_bf16 v[88:91], v[192:195], v[216:219], v[88:91]
	v_mfma_f32_16x16x32_bf16 v[84:87], v[200:203], v[216:219], v[84:87]
	v_mfma_f32_16x16x32_bf16 v[80:83], v[192:195], v[224:227], v[80:83]
	v_mfma_f32_16x16x32_bf16 v[76:79], v[200:203], v[224:227], v[76:79]
	v_mfma_f32_16x16x32_bf16 v[72:75], v[192:195], v[244:247], v[72:75]
	v_mfma_f32_16x16x32_bf16 v[68:71], v[200:203], v[244:247], v[68:71]
	v_mfma_f32_16x16x32_bf16 v[96:99], v[196:199], v[212:215], v[96:99]
	v_mfma_f32_16x16x32_bf16 v[92:95], v[204:207], v[212:215], v[92:95]
	v_mfma_f32_16x16x32_bf16 v[88:91], v[196:199], v[220:223], v[88:91]
	v_mfma_f32_16x16x32_bf16 v[84:87], v[204:207], v[220:223], v[84:87]
	v_mfma_f32_16x16x32_bf16 v[80:83], v[196:199], v[228:231], v[80:83]
	v_mfma_f32_16x16x32_bf16 v[76:79], v[204:207], v[228:231], v[76:79]
	v_mfma_f32_16x16x32_bf16 v[72:75], v[196:199], v[248:251], v[72:75]
	s_setprio 3
	s_barrier
; #define PG8_STAGE(bufoff, gbase, voff) do { _Pragma("unroll") for (int _i = 0; _i < 2; ++_i) \
;         __builtin_amdgcn_global_load_lds((const unsigned*)((const char*)(gbase) + (voff)[_i]), (PG8_LAS unsigned*)(lds + (bufoff) + ldsw + _i * 8192), 16, 0, 0); } while (0)
; #define PG8_LDA(dst, b, h) do { _Pragma("unroll") for (int m = 0; m < 4; ++m) _Pragma("unroll") for (int k = 0; k < 2; ++k) dst[m][k] = *(const PG8_LAS bf16x8*)(lds + PG8_SA(b, h) + aoff + m * 2048 + k * 1024); } while (0)
; #define PG8_MMA(ai, bj, At, Bt) do { __builtin_amdgcn_s_setprio(1); _Pragma("unroll") for (int m = 0; m < 4; ++m) _Pragma("unroll") for (int n = 0; n < 2; ++n) _Pragma("unroll") for (int k = 0; k < 2; ++k) \
;         acc[ai][bj][m][n] = __builtin_amdgcn_mfma_f32_16x16x32_bf16(Bt[n][k], At[m][k], acc[ai][bj][m][n], 0, 0, 0); __builtin_amdgcn_s_setprio(0); } while (0)
; #define PG8_WAIT_V(n) asm volatile("s_waitcnt vmcnt(" #n ")" ::: "memory")
; #define PG8_WAIT_L(n) asm volatile("s_waitcnt lgkmcnt(" #n ")" ::: "memory")
; #define PG8_BAR __builtin_amdgcn_s_barrier()
; #define PG8_SCHED __builtin_amdgcn_sched_barrier(0)
; template <class Epi, class Sched, bool ALIGN_EPI = false, bool SP2 = false>
; __device__ __forceinline__ void gemm_phase(PG8_LAS unsigned char* lds, const Gemm g, const Sched& S, const Epi& E) {
;     ...
;             PG8_LDA(At, 1, 1); PG8_STAGE(PG8_SB(1, 0), b3, voffB); PG8_STAGE(PG8_SB(1, 1), b3 + hstep, voffB); PG8_STAGE(PG8_SA(1, 0), a3, voffA);
;             PG8_WAIT_V(8); PG8_WAIT_L(0); PG8_BAR; PG8_MMA(1, 0, At, B0); PG8_MMA(1, 1, At, B1); PG8_BAR; PG8_SCHED;
;     ...
;         if constexpr (ALIGN_EPI) { if (wr == 0) PG8_BAR; }
	v_mfma_f32_16x16x32_bf16 v[68:71], v[204:207], v[248:251], v[68:71]
	s_setprio 0
	s_add_i32 s22, s50, s30
	v_lshl_add_u64 v[6:7], v[156:157], 0, s[54:55]
	s_mov_b32 m0, s22
	ds_read_b128 v[208:211], v161 offset:49152
	ds_read_b128 v[212:215], v161 offset:50176
	ds_read_b128 v[216:219], v161 offset:51200
	ds_read_b128 v[220:223], v161 offset:52224
	ds_read_b128 v[224:227], v161 offset:53248
	ds_read_b128 v[228:231], v161 offset:54272
	ds_read_b128 v[244:247], v161 offset:55296
	ds_read_b128 v[248:251], v161 offset:56320
	global_load_lds_dwordx4 v[6:7], off
	s_add_i32 m0, s22, 0x2000
	s_add_u32 s20, s20, 0x20080
	v_lshl_add_u64 v[6:7], v[232:233], 0, s[54:55]
	s_addc_u32 s21, s21, 0
	s_add_i32 s22, s51, s30
	global_load_lds_dwordx4 v[6:7], off
	v_lshl_add_u64 v[6:7], s[20:21], 0, v[136:137]
	s_mov_b32 m0, s22
	s_nop 0
	global_load_lds_dwordx4 v[6:7], off
	v_lshl_add_u64 v[6:7], s[20:21], 0, v[132:133]
	s_add_i32 m0, s22, 0x2000
	s_nop 0
	global_load_lds_dwordx4 v[6:7], off
	v_lshl_add_u64 v[6:7], v[236:237], 0, s[54:55]
	s_mov_b32 m0, s41
	s_nop 0
	global_load_lds_dwordx4 v[6:7], off
	v_lshl_add_u64 v[6:7], v[252:253], 0, s[54:55]
	s_mov_b32 m0, s42
	s_nop 0
	global_load_lds_dwordx4 v[6:7], off
	s_waitcnt vmcnt(8)
	s_waitcnt lgkmcnt(0)
	s_barrier
	s_setprio 1
	s_waitcnt lgkmcnt(0)
	v_mfma_f32_16x16x32_bf16 v[64:67], v[144:147], v[208:211], v[64:67]
	v_mfma_f32_16x16x32_bf16 v[60:63], v[152:155], v[208:211], v[60:63]
	v_mfma_f32_16x16x32_bf16 v[56:59], v[144:147], v[216:219], v[56:59]
	v_mfma_f32_16x16x32_bf16 v[52:55], v[152:155], v[216:219], v[52:55]
	v_mfma_f32_16x16x32_bf16 v[48:51], v[144:147], v[224:227], v[48:51]
	v_mfma_f32_16x16x32_bf16 v[44:47], v[152:155], v[224:227], v[44:47]
	v_mfma_f32_16x16x32_bf16 v[40:43], v[144:147], v[244:247], v[40:43]
	v_mfma_f32_16x16x32_bf16 v[36:39], v[152:155], v[244:247], v[36:39]
	v_mfma_f32_16x16x32_bf16 v[64:67], v[148:151], v[212:215], v[64:67]
	v_mfma_f32_16x16x32_bf16 v[60:63], v[162:165], v[212:215], v[60:63]
	v_mfma_f32_16x16x32_bf16 v[56:59], v[148:151], v[220:223], v[56:59]
	v_mfma_f32_16x16x32_bf16 v[52:55], v[162:165], v[220:223], v[52:55]
	v_mfma_f32_16x16x32_bf16 v[48:51], v[148:151], v[228:231], v[48:51]
	v_mfma_f32_16x16x32_bf16 v[44:47], v[162:165], v[228:231], v[44:47]
	v_mfma_f32_16x16x32_bf16 v[40:43], v[148:151], v[248:251], v[40:43]
	v_mfma_f32_16x16x32_bf16 v[36:39], v[162:165], v[248:251], v[36:39]
	s_setprio 0
	s_setprio 1
	v_mfma_f32_16x16x32_bf16 v[32:35], v[192:195], v[208:211], v[32:35]
	v_mfma_f32_16x16x32_bf16 v[28:31], v[200:203], v[208:211], v[28:31]
	v_mfma_f32_16x16x32_bf16 v[24:27], v[192:195], v[216:219], v[24:27]
	v_mfma_f32_16x16x32_bf16 v[20:23], v[200:203], v[216:219], v[20:23]
	v_mfma_f32_16x16x32_bf16 v[16:19], v[192:195], v[224:227], v[16:19]
	v_mfma_f32_16x16x32_bf16 v[12:15], v[200:203], v[224:227], v[12:15]
	v_mfma_f32_16x16x32_bf16 v[6:9], v[192:195], v[244:247], v[8:11]
	v_mfma_f32_16x16x32_bf16 v[2:5], v[200:203], v[244:247], v[2:5]
	v_mfma_f32_16x16x32_bf16 v[32:35], v[196:199], v[212:215], v[32:35]
	v_mfma_f32_16x16x32_bf16 v[28:31], v[204:207], v[212:215], v[28:31]
	v_mfma_f32_16x16x32_bf16 v[24:27], v[196:199], v[220:223], v[24:27]
	v_mfma_f32_16x16x32_bf16 v[20:23], v[204:207], v[220:223], v[20:23]
	v_mfma_f32_16x16x32_bf16 v[16:19], v[196:199], v[228:231], v[16:19]
	v_mfma_f32_16x16x32_bf16 v[12:15], v[204:207], v[228:231], v[12:15]
	v_mfma_f32_16x16x32_bf16 v[8:11], v[196:199], v[248:251], v[6:9]
	s_setprio 3
	s_barrier
	v_mfma_f32_16x16x32_bf16 v[4:7], v[204:207], v[248:251], v[2:5]
	s_setprio 0
	s_add_i32 s49, s49, 2
	s_add_u32 s47, s47, 0x100
	s_addc_u32 s48, s48, 0
	s_add_u32 s6, s6, 0x100
	s_addc_u32 s7, s7, 0
	s_cmp_gt_u32 s49, 5
	s_cbranch_scc0 .LBB0_514
	s_and_b64 vcc, exec, s[4:5]
	s_cbranch_vccz .LBB0_517
	s_barrier

; #define PG8_STAGE(bufoff, gbase, voff) do { _Pragma("unroll") for (int _i = 0; _i < 2; ++_i) \
;         __builtin_amdgcn_global_load_lds((const unsigned*)((const char*)(gbase) + (voff)[_i]), (PG8_LAS unsigned*)(lds + (bufoff) + ldsw + _i * 8192), 16, 0, 0); } while (0)
; #define PG8_LDA(dst, b, h) do { _Pragma("unroll") for (int m = 0; m < 4; ++m) _Pragma("unroll") for (int k = 0; k < 2; ++k) dst[m][k] = *(const PG8_LAS bf16x8*)(lds + PG8_SA(b, h) + aoff + m * 2048 + k * 1024); } while (0)
; #define PG8_LDB(dst, b, h) do { _Pragma("unroll") for (int n = 0; n < 2; ++n) _Pragma("unroll") for (int k = 0; k < 2; ++k) dst[n][k] = *(const PG8_LAS bf16x8*)(lds + PG8_SB(b, h) + boff + n * 2048 + k * 1024); } while (0)
; #define PG8_MMA(ai, bj, At, Bt) do { __builtin_amdgcn_s_setprio(1); _Pragma("unroll") for (int m = 0; m < 4; ++m) _Pragma("unroll") for (int n = 0; n < 2; ++n) _Pragma("unroll") for (int k = 0; k < 2; ++k) \
;         acc[ai][bj][m][n] = __builtin_amdgcn_mfma_f32_16x16x32_bf16(Bt[n][k], At[m][k], acc[ai][bj][m][n], 0, 0, 0); __builtin_amdgcn_s_setprio(0); } while (0)
; #define PG8_WAIT_V(n) asm volatile("s_waitcnt vmcnt(" #n ")" ::: "memory")
; #define PG8_BAR __builtin_amdgcn_s_barrier()
; template <class Epi, class Sched, bool ALIGN_EPI = false, bool SP2 = false>
; __device__ __forceinline__ void gemm_phase(PG8_LAS unsigned char* lds, const Gemm g, const Sched& S, const Epi& E) {
;     ...
;         for (int t = 0; t < nt; t += 2) {
;             const bool last = (t == nt - 2);
;             const char* a1 = cA + (size_t)(t + 1) * kstep;
;             const char* a2 = last ? nA : cA + (size_t)(t + 2) * kstep; const char* b2 = last ? nB : cB + (size_t)(t + 2) * kstep;
;             const char* a3 = a2 + kstep; const char* b3 = b2 + kstep;
;             if (last && has_next) S.a_ready(nxt);
;             if constexpr (SP2) {
;             PG8_LDB(B0, 0, 0); PG8_LDB(B1, 0, 1); PG8_SCHED; PG8_LDA(At, 0, 0); PG8_STAGE(PG8_SA(1, 1), a1 + hstep, voffA);
;             PG8_WAIT_V(8); PG8_WAIT_L(0); PG8_BAR; PG8_MMA(0, 0, At, B0); PG8_MMA(0, 1, At, B1); PG8_BAR; PG8_SCHED;
;             PG8_LDA(At, 0, 1); PG8_STAGE(PG8_SB(0, 0), b2, voffB); PG8_STAGE(PG8_SB(0, 1), b2 + hstep, voffB); PG8_STAGE(PG8_SA(0, 0), a2, voffA);
;             PG8_WAIT_V(8); PG8_WAIT_L(0); PG8_BAR; PG8_MMA(1, 0, At, B0); PG8_MMA(1, 1, At, B1); PG8_BAR; PG8_SCHED;
.LBB0_663:
	s_add_u32 s26, s24, 0xfffc0080
	s_addc_u32 s27, s25, -1
	s_add_i32 s51, 0, 0x10000
	s_cmp_eq_u32 s50, 12
	s_cselect_b32 s29, s15, s27
	s_cselect_b32 s28, s21, s26
	v_add_u32_e32 v144, s51, v147
	s_cselect_b32 s27, s13, s49
	s_cselect_b32 s26, s23, s48
	s_add_i32 s54, 0, 0x14000
	ds_read_b128 v[140:143], v144
	ds_read_b128 v[150:153], v144 offset:1024
	ds_read_b128 v[154:157], v144 offset:2048
	ds_read_b128 v[158:161], v144 offset:3072
	v_add_u32_e32 v144, s54, v147
	ds_read_b128 v[162:165], v144
	ds_read_b128 v[192:195], v144 offset:1024
	ds_read_b128 v[196:199], v144 offset:2048
	ds_read_b128 v[200:203], v144 offset:3072
	v_lshl_add_u64 v[144:145], s[24:25], 0, v[138:139]
	s_add_i32 m0, s38, 0xc000
	ds_read_b128 v[204:207], v149
	ds_read_b128 v[208:211], v149 offset:1024
	ds_read_b128 v[212:215], v149 offset:2048
	ds_read_b128 v[216:219], v149 offset:3072
	ds_read_b128 v[220:223], v149 offset:4096
	ds_read_b128 v[224:227], v149 offset:5120
	ds_read_b128 v[228:231], v149 offset:6144
	ds_read_b128 v[244:247], v149 offset:7168
	global_load_lds_dwordx4 v[144:145], off
	v_lshl_add_u64 v[144:145], s[24:25], 0, v[136:137]
	s_add_i32 m0, s38, 0xe000
	s_nop 0
	global_load_lds_dwordx4 v[144:145], off
	s_waitcnt vmcnt(8)
	s_waitcnt lgkmcnt(0)
	s_barrier
	s_setprio 1
	s_waitcnt lgkmcnt(0)
	v_mfma_f32_16x16x32_bf16 v[126:129], v[140:143], v[204:207], v[126:129]
	v_mfma_f32_16x16x32_bf16 v[122:125], v[154:157], v[204:207], v[122:125]
	v_mfma_f32_16x16x32_bf16 v[110:113], v[140:143], v[212:215], v[110:113]
	v_mfma_f32_16x16x32_bf16 v[106:109], v[154:157], v[212:215], v[106:109]
	v_mfma_f32_16x16x32_bf16 v[94:97], v[140:143], v[220:223], v[94:97]
	v_mfma_f32_16x16x32_bf16 v[90:93], v[154:157], v[220:223], v[90:93]
	v_mfma_f32_16x16x32_bf16 v[78:81], v[140:143], v[228:231], v[78:81]
	v_mfma_f32_16x16x32_bf16 v[74:77], v[154:157], v[228:231], v[74:77]
	v_mfma_f32_16x16x32_bf16 v[126:129], v[150:153], v[208:211], v[126:129]
	v_mfma_f32_16x16x32_bf16 v[122:125], v[158:161], v[208:211], v[122:125]
	v_mfma_f32_16x16x32_bf16 v[110:113], v[150:153], v[216:219], v[110:113]
	v_mfma_f32_16x16x32_bf16 v[106:109], v[158:161], v[216:219], v[106:109]
	v_mfma_f32_16x16x32_bf16 v[94:97], v[150:153], v[224:227], v[94:97]
	v_mfma_f32_16x16x32_bf16 v[90:93], v[158:161], v[224:227], v[90:93]
	v_mfma_f32_16x16x32_bf16 v[78:81], v[150:153], v[244:247], v[78:81]
	v_mfma_f32_16x16x32_bf16 v[74:77], v[158:161], v[244:247], v[74:77]
	s_setprio 0
	s_setprio 1
	v_mfma_f32_16x16x32_bf16 v[118:121], v[162:165], v[204:207], v[118:121]
	v_mfma_f32_16x16x32_bf16 v[114:117], v[196:199], v[204:207], v[114:117]
	v_mfma_f32_16x16x32_bf16 v[102:105], v[162:165], v[212:215], v[102:105]
	v_mfma_f32_16x16x32_bf16 v[98:101], v[196:199], v[212:215], v[98:101]
	v_mfma_f32_16x16x32_bf16 v[86:89], v[162:165], v[220:223], v[86:89]
	v_mfma_f32_16x16x32_bf16 v[82:85], v[196:199], v[220:223], v[82:85]
	v_mfma_f32_16x16x32_bf16 v[70:73], v[162:165], v[228:231], v[70:73]
	v_mfma_f32_16x16x32_bf16 v[66:69], v[196:199], v[228:231], v[66:69]
	v_mfma_f32_16x16x32_bf16 v[118:121], v[192:195], v[208:211], v[118:121]
	v_mfma_f32_16x16x32_bf16 v[114:117], v[200:203], v[208:211], v[114:117]
	v_mfma_f32_16x16x32_bf16 v[102:105], v[192:195], v[216:219], v[102:105]
	v_mfma_f32_16x16x32_bf16 v[98:101], v[200:203], v[216:219], v[98:101]
	v_mfma_f32_16x16x32_bf16 v[86:89], v[192:195], v[224:227], v[86:89]
	v_mfma_f32_16x16x32_bf16 v[82:85], v[200:203], v[224:227], v[82:85]
	v_mfma_f32_16x16x32_bf16 v[70:73], v[192:195], v[244:247], v[70:73]
	s_setprio 3
	s_barrier
	v_mfma_f32_16x16x32_bf16 v[66:69], v[200:203], v[244:247], v[66:69]
	s_setprio 0
	s_add_i32 s51, s51, s37
	v_lshl_add_u64 v[144:145], s[26:27], 0, v[0:1]
	s_mov_b32 m0, s51
	ds_read_b128 v[204:207], v149 offset:16384
	ds_read_b128 v[208:211], v149 offset:17408
	ds_read_b128 v[212:215], v149 offset:18432
	ds_read_b128 v[216:219], v149 offset:19456
	ds_read_b128 v[220:223], v149 offset:20480
	ds_read_b128 v[224:227], v149 offset:21504
	ds_read_b128 v[228:231], v149 offset:22528
	ds_read_b128 v[244:247], v149 offset:23552
	global_load_lds_dwordx4 v[144:145], off
	s_add_i32 m0, s51, 0x2000
	s_add_u32 s52, s26, 0x40000
	v_lshl_add_u64 v[232:233], s[26:27], 0, v[134:135]
	s_addc_u32 s53, s27, 0
	s_add_i32 s51, s54, s37
	global_load_lds_dwordx4 v[232:233], off
	v_lshl_add_u64 v[236:237], s[52:53], 0, v[0:1]
	s_mov_b32 m0, s51
	v_lshl_add_u64 v[248:249], s[28:29], 0, v[132:133]
	global_load_lds_dwordx4 v[236:237], off
	v_lshl_add_u64 v[236:237], s[52:53], 0, v[134:135]
	s_add_i32 m0, s51, 0x2000
	s_nop 0
	global_load_lds_dwordx4 v[236:237], off
	v_lshl_add_u64 v[236:237], s[28:29], 0, v[130:131]
	s_mov_b32 m0, s38
	s_nop 0
	global_load_lds_dwordx4 v[236:237], off
	s_mov_b32 m0, s39
	s_nop 0
	global_load_lds_dwordx4 v[248:249], off
	s_waitcnt vmcnt(8)
	s_waitcnt lgkmcnt(0)
	s_barrier
; #define PG8_STAGE(bufoff, gbase, voff) do { _Pragma("unroll") for (int _i = 0; _i < 2; ++_i) \
;         __builtin_amdgcn_global_load_lds((const unsigned*)((const char*)(gbase) + (voff)[_i]), (PG8_LAS unsigned*)(lds + (bufoff) + ldsw + _i * 8192), 16, 0, 0); } while (0)
; #define PG8_LDA(dst, b, h) do { _Pragma("unroll") for (int m = 0; m < 4; ++m) _Pragma("unroll") for (int k = 0; k < 2; ++k) dst[m][k] = *(const PG8_LAS bf16x8*)(lds + PG8_SA(b, h) + aoff + m * 2048 + k * 1024); } while (0)
; #define PG8_LDB(dst, b, h) do { _Pragma("unroll") for (int n = 0; n < 2; ++n) _Pragma("unroll") for (int k = 0; k < 2; ++k) dst[n][k] = *(const PG8_LAS bf16x8*)(lds + PG8_SB(b, h) + boff + n * 2048 + k * 1024); } while (0)
; #define PG8_MMA(ai, bj, At, Bt) do { __builtin_amdgcn_s_setprio(1); _Pragma("unroll") for (int m = 0; m < 4; ++m) _Pragma("unroll") for (int n = 0; n < 2; ++n) _Pragma("unroll") for (int k = 0; k < 2; ++k) \
;         acc[ai][bj][m][n] = __builtin_amdgcn_mfma_f32_16x16x32_bf16(Bt[n][k], At[m][k], acc[ai][bj][m][n], 0, 0, 0); __builtin_amdgcn_s_setprio(0); } while (0)
; #define PG8_WAIT_V(n) asm volatile("s_waitcnt vmcnt(" #n ")" ::: "memory")
; #define PG8_WAIT_L(n) asm volatile("s_waitcnt lgkmcnt(" #n ")" ::: "memory")
; #define PG8_BAR __builtin_amdgcn_s_barrier()
; #define PG8_SCHED __builtin_amdgcn_sched_barrier(0)
; template <class Epi, class Sched, bool ALIGN_EPI = false, bool SP2 = false>
; __device__ __forceinline__ void gemm_phase(PG8_LAS unsigned char* lds, const Gemm g, const Sched& S, const Epi& E) {
;     ...
;             PG8_LDA(At, 0, 1); PG8_STAGE(PG8_SB(0, 0), b2, voffB); PG8_STAGE(PG8_SB(0, 1), b2 + hstep, voffB); PG8_STAGE(PG8_SA(0, 0), a2, voffA);
;             PG8_WAIT_V(8); PG8_WAIT_L(0); PG8_BAR; PG8_MMA(1, 0, At, B0); PG8_MMA(1, 1, At, B1); PG8_BAR; PG8_SCHED;
;             PG8_LDB(B0, 1, 0); PG8_LDB(B1, 1, 1); PG8_SCHED; PG8_LDA(At, 1, 0); PG8_STAGE(PG8_SA(0, 1), a2 + hstep, voffA);
;             PG8_WAIT_V(8); PG8_WAIT_L(0); PG8_BAR; PG8_MMA(0, 0, At, B0); PG8_MMA(0, 1, At, B1); PG8_BAR; PG8_SCHED;
;             PG8_LDA(At, 1, 1); PG8_STAGE(PG8_SB(1, 0), b3, voffB); PG8_STAGE(PG8_SB(1, 1), b3 + hstep, voffB); PG8_STAGE(PG8_SA(1, 0), a3, voffA);
	s_setprio 1
	s_waitcnt lgkmcnt(0)
	v_mfma_f32_16x16x32_bf16 v[62:65], v[140:143], v[204:207], v[62:65]
	v_mfma_f32_16x16x32_bf16 v[58:61], v[154:157], v[204:207], v[58:61]
	v_mfma_f32_16x16x32_bf16 v[46:49], v[140:143], v[212:215], v[46:49]
	v_mfma_f32_16x16x32_bf16 v[42:45], v[154:157], v[212:215], v[42:45]
	v_mfma_f32_16x16x32_bf16 v[30:33], v[140:143], v[220:223], v[30:33]
	v_mfma_f32_16x16x32_bf16 v[26:29], v[154:157], v[220:223], v[26:29]
	v_mfma_f32_16x16x32_bf16 v[14:17], v[140:143], v[228:231], v[14:17]
	v_mfma_f32_16x16x32_bf16 v[10:13], v[154:157], v[228:231], v[10:13]
	v_mfma_f32_16x16x32_bf16 v[62:65], v[150:153], v[208:211], v[62:65]
	v_mfma_f32_16x16x32_bf16 v[58:61], v[158:161], v[208:211], v[58:61]
	v_mfma_f32_16x16x32_bf16 v[46:49], v[150:153], v[216:219], v[46:49]
	v_mfma_f32_16x16x32_bf16 v[42:45], v[158:161], v[216:219], v[42:45]
	v_mfma_f32_16x16x32_bf16 v[30:33], v[150:153], v[224:227], v[30:33]
	v_mfma_f32_16x16x32_bf16 v[26:29], v[158:161], v[224:227], v[26:29]
	v_mfma_f32_16x16x32_bf16 v[14:17], v[150:153], v[244:247], v[14:17]
	v_mfma_f32_16x16x32_bf16 v[10:13], v[158:161], v[244:247], v[10:13]
	s_setprio 0
	s_setprio 1
	v_mfma_f32_16x16x32_bf16 v[54:57], v[162:165], v[204:207], v[54:57]
	v_mfma_f32_16x16x32_bf16 v[50:53], v[196:199], v[204:207], v[50:53]
	v_mfma_f32_16x16x32_bf16 v[38:41], v[162:165], v[212:215], v[38:41]
	v_mfma_f32_16x16x32_bf16 v[34:37], v[196:199], v[212:215], v[34:37]
	v_mfma_f32_16x16x32_bf16 v[22:25], v[162:165], v[220:223], v[22:25]
	v_mfma_f32_16x16x32_bf16 v[18:21], v[196:199], v[220:223], v[18:21]
	v_mfma_f32_16x16x32_bf16 v[6:9], v[162:165], v[228:231], v[6:9]
	v_mfma_f32_16x16x32_bf16 v[2:5], v[196:199], v[228:231], v[2:5]
	v_mfma_f32_16x16x32_bf16 v[54:57], v[192:195], v[208:211], v[54:57]
	v_mfma_f32_16x16x32_bf16 v[50:53], v[200:203], v[208:211], v[50:53]
	v_mfma_f32_16x16x32_bf16 v[38:41], v[192:195], v[216:219], v[38:41]
	v_mfma_f32_16x16x32_bf16 v[34:37], v[200:203], v[216:219], v[34:37]
	v_mfma_f32_16x16x32_bf16 v[22:25], v[192:195], v[224:227], v[22:25]
	v_mfma_f32_16x16x32_bf16 v[18:21], v[200:203], v[224:227], v[18:21]
	v_mfma_f32_16x16x32_bf16 v[6:9], v[192:195], v[244:247], v[6:9]
	s_setprio 3
	s_barrier
	v_mfma_f32_16x16x32_bf16 v[2:5], v[200:203], v[244:247], v[2:5]
	s_setprio 0
	s_add_i32 s51, 0, 0x18000
	s_add_i32 s52, 0, 0x1c000
	v_add_u32_e32 v158, s51, v147
	v_add_u32_e32 v182, s52, v147
	ds_read_b128 v[140:143], v158
	ds_read_b128 v[150:153], v158 offset:1024
	ds_read_b128 v[154:157], v158 offset:2048
	ds_read_b128 v[158:161], v158 offset:3072
	ds_read_b128 v[162:165], v182
	ds_read_b128 v[192:195], v182 offset:1024
	ds_read_b128 v[196:199], v182 offset:2048
	ds_read_b128 v[200:203], v182 offset:3072
	s_add_u32 s28, s28, 0x40000
	s_addc_u32 s29, s29, 0
	s_mov_b32 m0, s40
	v_lshl_add_u64 v[250:251], s[28:29], 0, v[130:131]
	ds_read_b128 v[204:207], v149 offset:32768
	ds_read_b128 v[208:211], v149 offset:33792
	ds_read_b128 v[212:215], v149 offset:34816
	ds_read_b128 v[216:219], v149 offset:35840
	ds_read_b128 v[220:223], v149 offset:36864
	ds_read_b128 v[224:227], v149 offset:37888
	ds_read_b128 v[228:231], v149 offset:38912
	ds_read_b128 v[244:247], v149 offset:39936
	global_load_lds_dwordx4 v[250:251], off
	v_lshl_add_u64 v[250:251], s[28:29], 0, v[132:133]
	s_mov_b32 m0, s41
	s_nop 0
	global_load_lds_dwordx4 v[250:251], off
	s_waitcnt vmcnt(8)
	s_waitcnt lgkmcnt(0)
	s_barrier
	s_setprio 1
	s_waitcnt lgkmcnt(0)
	v_mfma_f32_16x16x32_bf16 v[126:129], v[140:143], v[204:207], v[126:129]
	v_mfma_f32_16x16x32_bf16 v[122:125], v[154:157], v[204:207], v[122:125]
	v_mfma_f32_16x16x32_bf16 v[110:113], v[140:143], v[212:215], v[110:113]
	v_mfma_f32_16x16x32_bf16 v[106:109], v[154:157], v[212:215], v[106:109]
	v_mfma_f32_16x16x32_bf16 v[94:97], v[140:143], v[220:223], v[94:97]
	v_mfma_f32_16x16x32_bf16 v[90:93], v[154:157], v[220:223], v[90:93]
	v_mfma_f32_16x16x32_bf16 v[78:81], v[140:143], v[228:231], v[78:81]
	v_mfma_f32_16x16x32_bf16 v[74:77], v[154:157], v[228:231], v[74:77]
	v_mfma_f32_16x16x32_bf16 v[126:129], v[150:153], v[208:211], v[126:129]
	v_mfma_f32_16x16x32_bf16 v[122:125], v[158:161], v[208:211], v[122:125]
	v_mfma_f32_16x16x32_bf16 v[110:113], v[150:153], v[216:219], v[110:113]
	v_mfma_f32_16x16x32_bf16 v[106:109], v[158:161], v[216:219], v[106:109]
	v_mfma_f32_16x16x32_bf16 v[94:97], v[150:153], v[224:227], v[94:97]
	v_mfma_f32_16x16x32_bf16 v[90:93], v[158:161], v[224:227], v[90:93]
	v_mfma_f32_16x16x32_bf16 v[78:81], v[150:153], v[244:247], v[78:81]
	v_mfma_f32_16x16x32_bf16 v[74:77], v[158:161], v[244:247], v[74:77]
	s_setprio 0
	s_setprio 1
	v_mfma_f32_16x16x32_bf16 v[118:121], v[162:165], v[204:207], v[118:121]
	v_mfma_f32_16x16x32_bf16 v[114:117], v[196:199], v[204:207], v[114:117]
	v_mfma_f32_16x16x32_bf16 v[102:105], v[162:165], v[212:215], v[102:105]
	v_mfma_f32_16x16x32_bf16 v[98:101], v[196:199], v[212:215], v[98:101]
	v_mfma_f32_16x16x32_bf16 v[86:89], v[162:165], v[220:223], v[86:89]
	v_mfma_f32_16x16x32_bf16 v[82:85], v[196:199], v[220:223], v[82:85]
	v_mfma_f32_16x16x32_bf16 v[70:73], v[162:165], v[228:231], v[70:73]
	v_mfma_f32_16x16x32_bf16 v[66:69], v[196:199], v[228:231], v[66:69]
	v_mfma_f32_16x16x32_bf16 v[118:121], v[192:195], v[208:211], v[118:121]
	v_mfma_f32_16x16x32_bf16 v[114:117], v[200:203], v[208:211], v[114:117]
	v_mfma_f32_16x16x32_bf16 v[102:105], v[192:195], v[216:219], v[102:105]
	v_mfma_f32_16x16x32_bf16 v[98:101], v[200:203], v[216:219], v[98:101]
	v_mfma_f32_16x16x32_bf16 v[86:89], v[192:195], v[224:227], v[86:89]
	v_mfma_f32_16x16x32_bf16 v[82:85], v[200:203], v[224:227], v[82:85]
	v_mfma_f32_16x16x32_bf16 v[70:73], v[192:195], v[244:247], v[70:73]
	s_setprio 3
	s_barrier
; #define PG8_STAGE(bufoff, gbase, voff) do { _Pragma("unroll") for (int _i = 0; _i < 2; ++_i) \
;         __builtin_amdgcn_global_load_lds((const unsigned*)((const char*)(gbase) + (voff)[_i]), (PG8_LAS unsigned*)(lds + (bufoff) + ldsw + _i * 8192), 16, 0, 0); } while (0)
; #define PG8_LDA(dst, b, h) do { _Pragma("unroll") for (int m = 0; m < 4; ++m) _Pragma("unroll") for (int k = 0; k < 2; ++k) dst[m][k] = *(const PG8_LAS bf16x8*)(lds + PG8_SA(b, h) + aoff + m * 2048 + k * 1024); } while (0)
; #define PG8_MMA(ai, bj, At, Bt) do { __builtin_amdgcn_s_setprio(1); _Pragma("unroll") for (int m = 0; m < 4; ++m) _Pragma("unroll") for (int n = 0; n < 2; ++n) _Pragma("unroll") for (int k = 0; k < 2; ++k) \
;         acc[ai][bj][m][n] = __builtin_amdgcn_mfma_f32_16x16x32_bf16(Bt[n][k], At[m][k], acc[ai][bj][m][n], 0, 0, 0); __builtin_amdgcn_s_setprio(0); } while (0)
; #define PG8_WAIT_V(n) asm volatile("s_waitcnt vmcnt(" #n ")" ::: "memory")
; #define PG8_WAIT_L(n) asm volatile("s_waitcnt lgkmcnt(" #n ")" ::: "memory")
; #define PG8_BAR __builtin_amdgcn_s_barrier()
; #define PG8_SCHED __builtin_amdgcn_sched_barrier(0)
; template <class Epi, class Sched, bool ALIGN_EPI = false, bool SP2 = false>
; __device__ __forceinline__ void gemm_phase(PG8_LAS unsigned char* lds, const Gemm g, const Sched& S, const Epi& E) {
;     ...
;             PG8_LDA(At, 1, 1); PG8_STAGE(PG8_SB(1, 0), b3, voffB); PG8_STAGE(PG8_SB(1, 1), b3 + hstep, voffB); PG8_STAGE(PG8_SA(1, 0), a3, voffA);
;             PG8_WAIT_V(8); PG8_WAIT_L(0); PG8_BAR; PG8_MMA(1, 0, At, B0); PG8_MMA(1, 1, At, B1); PG8_BAR; PG8_SCHED;
;     ...
;         if constexpr (ALIGN_EPI) { if (wr == 0) PG8_BAR; }
	v_mfma_f32_16x16x32_bf16 v[66:69], v[200:203], v[244:247], v[66:69]
	s_setprio 0
	s_add_i32 s28, s51, s37
	v_lshl_add_u64 v[144:145], v[144:145], 0, s[56:57]
	s_mov_b32 m0, s28
	ds_read_b128 v[204:207], v149 offset:49152
	ds_read_b128 v[208:211], v149 offset:50176
	ds_read_b128 v[212:215], v149 offset:51200
	ds_read_b128 v[216:219], v149 offset:52224
	ds_read_b128 v[220:223], v149 offset:53248
	ds_read_b128 v[224:227], v149 offset:54272
	ds_read_b128 v[228:231], v149 offset:55296
	ds_read_b128 v[244:247], v149 offset:56320
	global_load_lds_dwordx4 v[144:145], off
	s_add_i32 m0, s28, 0x2000
	s_add_u32 s26, s26, 0x40080
	v_lshl_add_u64 v[144:145], v[232:233], 0, s[56:57]
	s_addc_u32 s27, s27, 0
	s_add_i32 s28, s52, s37
	global_load_lds_dwordx4 v[144:145], off
	v_lshl_add_u64 v[144:145], s[26:27], 0, v[0:1]
	s_mov_b32 m0, s28
	s_nop 0
	global_load_lds_dwordx4 v[144:145], off
	v_lshl_add_u64 v[144:145], s[26:27], 0, v[134:135]
	s_add_i32 m0, s28, 0x2000
	s_nop 0
	global_load_lds_dwordx4 v[144:145], off
	v_lshl_add_u64 v[144:145], v[236:237], 0, s[56:57]
	s_mov_b32 m0, s43
	s_nop 0
	global_load_lds_dwordx4 v[144:145], off
	v_lshl_add_u64 v[144:145], v[248:249], 0, s[56:57]
	s_mov_b32 m0, s44
	s_nop 0
	global_load_lds_dwordx4 v[144:145], off
	s_waitcnt vmcnt(8)
	s_waitcnt lgkmcnt(0)
	s_barrier
	s_setprio 1
	s_waitcnt lgkmcnt(0)
	v_mfma_f32_16x16x32_bf16 v[62:65], v[140:143], v[204:207], v[62:65]
	v_mfma_f32_16x16x32_bf16 v[58:61], v[154:157], v[204:207], v[58:61]
	v_mfma_f32_16x16x32_bf16 v[46:49], v[140:143], v[212:215], v[46:49]
	v_mfma_f32_16x16x32_bf16 v[42:45], v[154:157], v[212:215], v[42:45]
	v_mfma_f32_16x16x32_bf16 v[30:33], v[140:143], v[220:223], v[30:33]
	v_mfma_f32_16x16x32_bf16 v[26:29], v[154:157], v[220:223], v[26:29]
	v_mfma_f32_16x16x32_bf16 v[14:17], v[140:143], v[228:231], v[14:17]
	v_mfma_f32_16x16x32_bf16 v[10:13], v[154:157], v[228:231], v[10:13]
	v_mfma_f32_16x16x32_bf16 v[62:65], v[150:153], v[208:211], v[62:65]
	v_mfma_f32_16x16x32_bf16 v[58:61], v[158:161], v[208:211], v[58:61]
	v_mfma_f32_16x16x32_bf16 v[46:49], v[150:153], v[216:219], v[46:49]
	v_mfma_f32_16x16x32_bf16 v[42:45], v[158:161], v[216:219], v[42:45]
	v_mfma_f32_16x16x32_bf16 v[30:33], v[150:153], v[224:227], v[30:33]
	v_mfma_f32_16x16x32_bf16 v[26:29], v[158:161], v[224:227], v[26:29]
	v_mfma_f32_16x16x32_bf16 v[14:17], v[150:153], v[244:247], v[14:17]
	v_mfma_f32_16x16x32_bf16 v[10:13], v[158:161], v[244:247], v[10:13]
	s_setprio 0
	s_setprio 1
	v_mfma_f32_16x16x32_bf16 v[54:57], v[162:165], v[204:207], v[54:57]
	v_mfma_f32_16x16x32_bf16 v[50:53], v[196:199], v[204:207], v[50:53]
	v_mfma_f32_16x16x32_bf16 v[38:41], v[162:165], v[212:215], v[38:41]
	v_mfma_f32_16x16x32_bf16 v[34:37], v[196:199], v[212:215], v[34:37]
	v_mfma_f32_16x16x32_bf16 v[22:25], v[162:165], v[220:223], v[22:25]
	v_mfma_f32_16x16x32_bf16 v[18:21], v[196:199], v[220:223], v[18:21]
	v_mfma_f32_16x16x32_bf16 v[6:9], v[162:165], v[228:231], v[6:9]
	v_mfma_f32_16x16x32_bf16 v[2:5], v[196:199], v[228:231], v[2:5]
	v_mfma_f32_16x16x32_bf16 v[54:57], v[192:195], v[208:211], v[54:57]
	v_mfma_f32_16x16x32_bf16 v[50:53], v[200:203], v[208:211], v[50:53]
	v_mfma_f32_16x16x32_bf16 v[38:41], v[192:195], v[216:219], v[38:41]
	v_mfma_f32_16x16x32_bf16 v[34:37], v[200:203], v[216:219], v[34:37]
	v_mfma_f32_16x16x32_bf16 v[22:25], v[192:195], v[224:227], v[22:25]
	v_mfma_f32_16x16x32_bf16 v[18:21], v[200:203], v[224:227], v[18:21]
	v_mfma_f32_16x16x32_bf16 v[6:9], v[192:195], v[244:247], v[6:9]
	s_setprio 3
	s_barrier
	v_mfma_f32_16x16x32_bf16 v[2:5], v[200:203], v[244:247], v[2:5]
	s_setprio 0
	s_add_i32 s50, s50, 2
	s_add_u32 s48, s48, 0x100
	s_addc_u32 s49, s49, 0
	s_add_u32 s24, s24, 0x100
	s_addc_u32 s25, s25, 0
	s_cmp_gt_u32 s50, 13
	s_cbranch_scc0 .LBB0_663
	s_and_b64 vcc, exec, s[10:11]
	s_cbranch_vccz .LBB0_666
	s_barrier

; #define PG8_STAGE(bufoff, gbase, voff) do { _Pragma("unroll") for (int _i = 0; _i < 2; ++_i) \
;         __builtin_amdgcn_global_load_lds((const unsigned*)((const char*)(gbase) + (voff)[_i]), (PG8_LAS unsigned*)(lds + (bufoff) + ldsw + _i * 8192), 16, 0, 0); } while (0)
; #define PG8_LDA(dst, b, h) do { _Pragma("unroll") for (int m = 0; m < 4; ++m) _Pragma("unroll") for (int k = 0; k < 2; ++k) dst[m][k] = *(const PG8_LAS bf16x8*)(lds + PG8_SA(b, h) + aoff + m * 2048 + k * 1024); } while (0)
; #define PG8_LDB(dst, b, h) do { _Pragma("unroll") for (int n = 0; n < 2; ++n) _Pragma("unroll") for (int k = 0; k < 2; ++k) dst[n][k] = *(const PG8_LAS bf16x8*)(lds + PG8_SB(b, h) + boff + n * 2048 + k * 1024); } while (0)
; #define PG8_MMA(ai, bj, At, Bt) do { __builtin_amdgcn_s_setprio(1); _Pragma("unroll") for (int m = 0; m < 4; ++m) _Pragma("unroll") for (int n = 0; n < 2; ++n) _Pragma("unroll") for (int k = 0; k < 2; ++k) \
;         acc[ai][bj][m][n] = __builtin_amdgcn_mfma_f32_16x16x32_bf16(Bt[n][k], At[m][k], acc[ai][bj][m][n], 0, 0, 0); __builtin_amdgcn_s_setprio(0); } while (0)
; #define PG8_WAIT_V(n) asm volatile("s_waitcnt vmcnt(" #n ")" ::: "memory")
; #define PG8_BAR __builtin_amdgcn_s_barrier()
; template <class Epi, class Sched, bool ALIGN_EPI = false, bool SP2 = false>
; __device__ __forceinline__ void gemm_phase(PG8_LAS unsigned char* lds, const Gemm g, const Sched& S, const Epi& E) {
;     ...
;         for (int t = 0; t < nt; t += 2) {
;             const bool last = (t == nt - 2);
;             const char* a1 = cA + (size_t)(t + 1) * kstep;
;             const char* a2 = last ? nA : cA + (size_t)(t + 2) * kstep; const char* b2 = last ? nB : cB + (size_t)(t + 2) * kstep;
;             const char* a3 = a2 + kstep; const char* b3 = b2 + kstep;
;             if (last && has_next) S.a_ready(nxt);
;             if constexpr (SP2) {
;             PG8_LDB(B0, 0, 0); PG8_LDB(B1, 0, 1); PG8_SCHED; PG8_LDA(At, 0, 0); PG8_STAGE(PG8_SA(1, 1), a1 + hstep, voffA);
;             PG8_WAIT_V(8); PG8_WAIT_L(0); PG8_BAR; PG8_MMA(0, 0, At, B0); PG8_MMA(0, 1, At, B1); PG8_BAR; PG8_SCHED;
;             PG8_LDA(At, 0, 1); PG8_STAGE(PG8_SB(0, 0), b2, voffB); PG8_STAGE(PG8_SB(0, 1), b2 + hstep, voffB); PG8_STAGE(PG8_SA(0, 0), a2, voffA);
;             PG8_WAIT_V(8); PG8_WAIT_L(0); PG8_BAR; PG8_MMA(1, 0, At, B0); PG8_MMA(1, 1, At, B1); PG8_BAR; PG8_SCHED;
.LBB0_752:
	s_add_u32 s22, s20, 0xfffc0080
	s_addc_u32 s23, s21, -1
	s_add_i32 s48, 0, 0x10000
	s_cmp_eq_u32 s47, 12
	s_cselect_b32 s25, s13, s23
	s_cselect_b32 s24, s43, s22
	v_add_u32_e32 v144, s48, v147
	s_cselect_b32 s23, s11, s46
	s_cselect_b32 s22, s44, s45
	s_add_i32 s50, 0, 0x14000
	ds_read_b128 v[140:143], v144
	ds_read_b128 v[150:153], v144 offset:1024
	ds_read_b128 v[154:157], v144 offset:2048
	ds_read_b128 v[158:161], v144 offset:3072
	v_add_u32_e32 v144, s50, v147
	ds_read_b128 v[162:165], v144
	ds_read_b128 v[192:195], v144 offset:1024
	ds_read_b128 v[196:199], v144 offset:2048
	ds_read_b128 v[200:203], v144 offset:3072
	v_lshl_add_u64 v[144:145], s[20:21], 0, v[138:139]
	s_add_i32 m0, s35, 0xc000
	ds_read_b128 v[204:207], v149
	ds_read_b128 v[208:211], v149 offset:1024
	ds_read_b128 v[212:215], v149 offset:2048
	ds_read_b128 v[216:219], v149 offset:3072
	ds_read_b128 v[220:223], v149 offset:4096
	ds_read_b128 v[224:227], v149 offset:5120
	ds_read_b128 v[228:231], v149 offset:6144
	ds_read_b128 v[244:247], v149 offset:7168
	global_load_lds_dwordx4 v[144:145], off
	v_lshl_add_u64 v[144:145], s[20:21], 0, v[136:137]
	s_add_i32 m0, s35, 0xe000
	s_nop 0
	global_load_lds_dwordx4 v[144:145], off
	s_waitcnt vmcnt(8)
	s_waitcnt lgkmcnt(0)
	s_barrier
	s_setprio 1
	s_waitcnt lgkmcnt(0)
	v_mfma_f32_16x16x32_bf16 v[126:129], v[140:143], v[204:207], v[126:129]
	v_mfma_f32_16x16x32_bf16 v[122:125], v[154:157], v[204:207], v[122:125]
	v_mfma_f32_16x16x32_bf16 v[110:113], v[140:143], v[212:215], v[110:113]
	v_mfma_f32_16x16x32_bf16 v[106:109], v[154:157], v[212:215], v[106:109]
	v_mfma_f32_16x16x32_bf16 v[94:97], v[140:143], v[220:223], v[94:97]
	v_mfma_f32_16x16x32_bf16 v[90:93], v[154:157], v[220:223], v[90:93]
	v_mfma_f32_16x16x32_bf16 v[78:81], v[140:143], v[228:231], v[78:81]
	v_mfma_f32_16x16x32_bf16 v[74:77], v[154:157], v[228:231], v[74:77]
	v_mfma_f32_16x16x32_bf16 v[126:129], v[150:153], v[208:211], v[126:129]
	v_mfma_f32_16x16x32_bf16 v[122:125], v[158:161], v[208:211], v[122:125]
	v_mfma_f32_16x16x32_bf16 v[110:113], v[150:153], v[216:219], v[110:113]
	v_mfma_f32_16x16x32_bf16 v[106:109], v[158:161], v[216:219], v[106:109]
	v_mfma_f32_16x16x32_bf16 v[94:97], v[150:153], v[224:227], v[94:97]
	v_mfma_f32_16x16x32_bf16 v[90:93], v[158:161], v[224:227], v[90:93]
	v_mfma_f32_16x16x32_bf16 v[78:81], v[150:153], v[244:247], v[78:81]
	v_mfma_f32_16x16x32_bf16 v[74:77], v[158:161], v[244:247], v[74:77]
	s_setprio 0
	s_setprio 1
	v_mfma_f32_16x16x32_bf16 v[118:121], v[162:165], v[204:207], v[118:121]
	v_mfma_f32_16x16x32_bf16 v[114:117], v[196:199], v[204:207], v[114:117]
	v_mfma_f32_16x16x32_bf16 v[102:105], v[162:165], v[212:215], v[102:105]
	v_mfma_f32_16x16x32_bf16 v[98:101], v[196:199], v[212:215], v[98:101]
	v_mfma_f32_16x16x32_bf16 v[86:89], v[162:165], v[220:223], v[86:89]
	v_mfma_f32_16x16x32_bf16 v[82:85], v[196:199], v[220:223], v[82:85]
	v_mfma_f32_16x16x32_bf16 v[70:73], v[162:165], v[228:231], v[70:73]
	v_mfma_f32_16x16x32_bf16 v[66:69], v[196:199], v[228:231], v[66:69]
	v_mfma_f32_16x16x32_bf16 v[118:121], v[192:195], v[208:211], v[118:121]
	v_mfma_f32_16x16x32_bf16 v[114:117], v[200:203], v[208:211], v[114:117]
	v_mfma_f32_16x16x32_bf16 v[102:105], v[192:195], v[216:219], v[102:105]
	v_mfma_f32_16x16x32_bf16 v[98:101], v[200:203], v[216:219], v[98:101]
	v_mfma_f32_16x16x32_bf16 v[86:89], v[192:195], v[224:227], v[86:89]
	v_mfma_f32_16x16x32_bf16 v[82:85], v[200:203], v[224:227], v[82:85]
	v_mfma_f32_16x16x32_bf16 v[70:73], v[192:195], v[244:247], v[70:73]
	s_setprio 3
	s_barrier
	v_mfma_f32_16x16x32_bf16 v[66:69], v[200:203], v[244:247], v[66:69]
	s_setprio 0
	s_add_i32 s48, s48, s33
	v_lshl_add_u64 v[144:145], s[22:23], 0, v[0:1]
	s_mov_b32 m0, s48
	ds_read_b128 v[204:207], v149 offset:16384
	ds_read_b128 v[208:211], v149 offset:17408
	ds_read_b128 v[212:215], v149 offset:18432
	ds_read_b128 v[216:219], v149 offset:19456
	ds_read_b128 v[220:223], v149 offset:20480
	ds_read_b128 v[224:227], v149 offset:21504
	ds_read_b128 v[228:231], v149 offset:22528
	ds_read_b128 v[244:247], v149 offset:23552
	global_load_lds_dwordx4 v[144:145], off
	s_add_i32 m0, s48, 0x2000
	s_add_u32 s48, s22, 0x40000
	v_lshl_add_u64 v[232:233], s[22:23], 0, v[130:131]
	s_addc_u32 s49, s23, 0
	s_add_i32 s50, s50, s33
	global_load_lds_dwordx4 v[232:233], off
	v_lshl_add_u64 v[236:237], s[48:49], 0, v[0:1]
	s_mov_b32 m0, s50
	v_lshl_add_u64 v[248:249], s[24:25], 0, v[132:133]
	global_load_lds_dwordx4 v[236:237], off
	v_lshl_add_u64 v[236:237], s[48:49], 0, v[130:131]
	s_add_i32 m0, s50, 0x2000
	s_nop 0
	global_load_lds_dwordx4 v[236:237], off
	v_lshl_add_u64 v[236:237], s[24:25], 0, v[134:135]
	s_mov_b32 m0, s35
	s_nop 0
	global_load_lds_dwordx4 v[236:237], off
	s_mov_b32 m0, s36
	s_nop 0
	global_load_lds_dwordx4 v[248:249], off
	s_waitcnt vmcnt(8)
	s_waitcnt lgkmcnt(0)
	s_barrier
; #define PG8_STAGE(bufoff, gbase, voff) do { _Pragma("unroll") for (int _i = 0; _i < 2; ++_i) \
;         __builtin_amdgcn_global_load_lds((const unsigned*)((const char*)(gbase) + (voff)[_i]), (PG8_LAS unsigned*)(lds + (bufoff) + ldsw + _i * 8192), 16, 0, 0); } while (0)
; #define PG8_LDA(dst, b, h) do { _Pragma("unroll") for (int m = 0; m < 4; ++m) _Pragma("unroll") for (int k = 0; k < 2; ++k) dst[m][k] = *(const PG8_LAS bf16x8*)(lds + PG8_SA(b, h) + aoff + m * 2048 + k * 1024); } while (0)
; #define PG8_LDB(dst, b, h) do { _Pragma("unroll") for (int n = 0; n < 2; ++n) _Pragma("unroll") for (int k = 0; k < 2; ++k) dst[n][k] = *(const PG8_LAS bf16x8*)(lds + PG8_SB(b, h) + boff + n * 2048 + k * 1024); } while (0)
; #define PG8_MMA(ai, bj, At, Bt) do { __builtin_amdgcn_s_setprio(1); _Pragma("unroll") for (int m = 0; m < 4; ++m) _Pragma("unroll") for (int n = 0; n < 2; ++n) _Pragma("unroll") for (int k = 0; k < 2; ++k) \
;         acc[ai][bj][m][n] = __builtin_amdgcn_mfma_f32_16x16x32_bf16(Bt[n][k], At[m][k], acc[ai][bj][m][n], 0, 0, 0); __builtin_amdgcn_s_setprio(0); } while (0)
; #define PG8_WAIT_V(n) asm volatile("s_waitcnt vmcnt(" #n ")" ::: "memory")
; #define PG8_WAIT_L(n) asm volatile("s_waitcnt lgkmcnt(" #n ")" ::: "memory")
; #define PG8_BAR __builtin_amdgcn_s_barrier()
; #define PG8_SCHED __builtin_amdgcn_sched_barrier(0)
; template <class Epi, class Sched, bool ALIGN_EPI = false, bool SP2 = false>
; __device__ __forceinline__ void gemm_phase(PG8_LAS unsigned char* lds, const Gemm g, const Sched& S, const Epi& E) {
;     ...
;             PG8_LDA(At, 0, 1); PG8_STAGE(PG8_SB(0, 0), b2, voffB); PG8_STAGE(PG8_SB(0, 1), b2 + hstep, voffB); PG8_STAGE(PG8_SA(0, 0), a2, voffA);
;             PG8_WAIT_V(8); PG8_WAIT_L(0); PG8_BAR; PG8_MMA(1, 0, At, B0); PG8_MMA(1, 1, At, B1); PG8_BAR; PG8_SCHED;
;             PG8_LDB(B0, 1, 0); PG8_LDB(B1, 1, 1); PG8_SCHED; PG8_LDA(At, 1, 0); PG8_STAGE(PG8_SA(0, 1), a2 + hstep, voffA);
;             PG8_WAIT_V(8); PG8_WAIT_L(0); PG8_BAR; PG8_MMA(0, 0, At, B0); PG8_MMA(0, 1, At, B1); PG8_BAR; PG8_SCHED;
;             PG8_LDA(At, 1, 1); PG8_STAGE(PG8_SB(1, 0), b3, voffB); PG8_STAGE(PG8_SB(1, 1), b3 + hstep, voffB); PG8_STAGE(PG8_SA(1, 0), a3, voffA);
	s_setprio 1
	s_waitcnt lgkmcnt(0)
	v_mfma_f32_16x16x32_bf16 v[62:65], v[140:143], v[204:207], v[62:65]
	v_mfma_f32_16x16x32_bf16 v[58:61], v[154:157], v[204:207], v[58:61]
	v_mfma_f32_16x16x32_bf16 v[46:49], v[140:143], v[212:215], v[46:49]
	v_mfma_f32_16x16x32_bf16 v[42:45], v[154:157], v[212:215], v[42:45]
	v_mfma_f32_16x16x32_bf16 v[30:33], v[140:143], v[220:223], v[30:33]
	v_mfma_f32_16x16x32_bf16 v[26:29], v[154:157], v[220:223], v[26:29]
	v_mfma_f32_16x16x32_bf16 v[14:17], v[140:143], v[228:231], v[14:17]
	v_mfma_f32_16x16x32_bf16 v[10:13], v[154:157], v[228:231], v[10:13]
	v_mfma_f32_16x16x32_bf16 v[62:65], v[150:153], v[208:211], v[62:65]
	v_mfma_f32_16x16x32_bf16 v[58:61], v[158:161], v[208:211], v[58:61]
	v_mfma_f32_16x16x32_bf16 v[46:49], v[150:153], v[216:219], v[46:49]
	v_mfma_f32_16x16x32_bf16 v[42:45], v[158:161], v[216:219], v[42:45]
	v_mfma_f32_16x16x32_bf16 v[30:33], v[150:153], v[224:227], v[30:33]
	v_mfma_f32_16x16x32_bf16 v[26:29], v[158:161], v[224:227], v[26:29]
	v_mfma_f32_16x16x32_bf16 v[14:17], v[150:153], v[244:247], v[14:17]
	v_mfma_f32_16x16x32_bf16 v[10:13], v[158:161], v[244:247], v[10:13]
	s_setprio 0
	s_setprio 1
	v_mfma_f32_16x16x32_bf16 v[54:57], v[162:165], v[204:207], v[54:57]
	v_mfma_f32_16x16x32_bf16 v[50:53], v[196:199], v[204:207], v[50:53]
	v_mfma_f32_16x16x32_bf16 v[38:41], v[162:165], v[212:215], v[38:41]
	v_mfma_f32_16x16x32_bf16 v[34:37], v[196:199], v[212:215], v[34:37]
	v_mfma_f32_16x16x32_bf16 v[22:25], v[162:165], v[220:223], v[22:25]
	v_mfma_f32_16x16x32_bf16 v[18:21], v[196:199], v[220:223], v[18:21]
	v_mfma_f32_16x16x32_bf16 v[6:9], v[162:165], v[228:231], v[6:9]
	v_mfma_f32_16x16x32_bf16 v[2:5], v[196:199], v[228:231], v[2:5]
	v_mfma_f32_16x16x32_bf16 v[54:57], v[192:195], v[208:211], v[54:57]
	v_mfma_f32_16x16x32_bf16 v[50:53], v[200:203], v[208:211], v[50:53]
	v_mfma_f32_16x16x32_bf16 v[38:41], v[192:195], v[216:219], v[38:41]
	v_mfma_f32_16x16x32_bf16 v[34:37], v[200:203], v[216:219], v[34:37]
	v_mfma_f32_16x16x32_bf16 v[22:25], v[192:195], v[224:227], v[22:25]
	v_mfma_f32_16x16x32_bf16 v[18:21], v[200:203], v[224:227], v[18:21]
	v_mfma_f32_16x16x32_bf16 v[6:9], v[192:195], v[244:247], v[6:9]
	s_setprio 3
	s_barrier
	v_mfma_f32_16x16x32_bf16 v[2:5], v[200:203], v[244:247], v[2:5]
	s_setprio 0
	s_add_i32 s48, 0, 0x18000
	s_add_i32 s49, 0, 0x1c000
	v_add_u32_e32 v158, s48, v147
	v_add_u32_e32 v182, s49, v147
	ds_read_b128 v[140:143], v158
	ds_read_b128 v[150:153], v158 offset:1024
	ds_read_b128 v[154:157], v158 offset:2048
	ds_read_b128 v[158:161], v158 offset:3072
	ds_read_b128 v[162:165], v182
	ds_read_b128 v[192:195], v182 offset:1024
	ds_read_b128 v[196:199], v182 offset:2048
	ds_read_b128 v[200:203], v182 offset:3072
	s_add_u32 s24, s24, 0x40000
	s_addc_u32 s25, s25, 0
	s_mov_b32 m0, s37
	v_lshl_add_u64 v[250:251], s[24:25], 0, v[134:135]
	ds_read_b128 v[204:207], v149 offset:32768
	ds_read_b128 v[208:211], v149 offset:33792
	ds_read_b128 v[212:215], v149 offset:34816
	ds_read_b128 v[216:219], v149 offset:35840
	ds_read_b128 v[220:223], v149 offset:36864
	ds_read_b128 v[224:227], v149 offset:37888
	ds_read_b128 v[228:231], v149 offset:38912
	ds_read_b128 v[244:247], v149 offset:39936
	global_load_lds_dwordx4 v[250:251], off
	v_lshl_add_u64 v[250:251], s[24:25], 0, v[132:133]
	s_mov_b32 m0, s38
	s_nop 0
	global_load_lds_dwordx4 v[250:251], off
	s_waitcnt vmcnt(8)
	s_waitcnt lgkmcnt(0)
	s_barrier
	s_setprio 1
	s_waitcnt lgkmcnt(0)
	v_mfma_f32_16x16x32_bf16 v[126:129], v[140:143], v[204:207], v[126:129]
	v_mfma_f32_16x16x32_bf16 v[122:125], v[154:157], v[204:207], v[122:125]
	v_mfma_f32_16x16x32_bf16 v[110:113], v[140:143], v[212:215], v[110:113]
	v_mfma_f32_16x16x32_bf16 v[106:109], v[154:157], v[212:215], v[106:109]
	v_mfma_f32_16x16x32_bf16 v[94:97], v[140:143], v[220:223], v[94:97]
	v_mfma_f32_16x16x32_bf16 v[90:93], v[154:157], v[220:223], v[90:93]
	v_mfma_f32_16x16x32_bf16 v[78:81], v[140:143], v[228:231], v[78:81]
	v_mfma_f32_16x16x32_bf16 v[74:77], v[154:157], v[228:231], v[74:77]
	v_mfma_f32_16x16x32_bf16 v[126:129], v[150:153], v[208:211], v[126:129]
	v_mfma_f32_16x16x32_bf16 v[122:125], v[158:161], v[208:211], v[122:125]
	v_mfma_f32_16x16x32_bf16 v[110:113], v[150:153], v[216:219], v[110:113]
	v_mfma_f32_16x16x32_bf16 v[106:109], v[158:161], v[216:219], v[106:109]
	v_mfma_f32_16x16x32_bf16 v[94:97], v[150:153], v[224:227], v[94:97]
	v_mfma_f32_16x16x32_bf16 v[90:93], v[158:161], v[224:227], v[90:93]
	v_mfma_f32_16x16x32_bf16 v[78:81], v[150:153], v[244:247], v[78:81]
	v_mfma_f32_16x16x32_bf16 v[74:77], v[158:161], v[244:247], v[74:77]
	s_setprio 0
	s_setprio 1
	v_mfma_f32_16x16x32_bf16 v[118:121], v[162:165], v[204:207], v[118:121]
	v_mfma_f32_16x16x32_bf16 v[114:117], v[196:199], v[204:207], v[114:117]
	v_mfma_f32_16x16x32_bf16 v[102:105], v[162:165], v[212:215], v[102:105]
	v_mfma_f32_16x16x32_bf16 v[98:101], v[196:199], v[212:215], v[98:101]
	v_mfma_f32_16x16x32_bf16 v[86:89], v[162:165], v[220:223], v[86:89]
	v_mfma_f32_16x16x32_bf16 v[82:85], v[196:199], v[220:223], v[82:85]
	v_mfma_f32_16x16x32_bf16 v[70:73], v[162:165], v[228:231], v[70:73]
	v_mfma_f32_16x16x32_bf16 v[66:69], v[196:199], v[228:231], v[66:69]
	v_mfma_f32_16x16x32_bf16 v[118:121], v[192:195], v[208:211], v[118:121]
	v_mfma_f32_16x16x32_bf16 v[114:117], v[200:203], v[208:211], v[114:117]
	v_mfma_f32_16x16x32_bf16 v[102:105], v[192:195], v[216:219], v[102:105]
	v_mfma_f32_16x16x32_bf16 v[98:101], v[200:203], v[216:219], v[98:101]
	v_mfma_f32_16x16x32_bf16 v[86:89], v[192:195], v[224:227], v[86:89]
	v_mfma_f32_16x16x32_bf16 v[82:85], v[200:203], v[224:227], v[82:85]
	v_mfma_f32_16x16x32_bf16 v[70:73], v[192:195], v[244:247], v[70:73]
	s_setprio 3
	s_barrier
; #define PG8_STAGE(bufoff, gbase, voff) do { _Pragma("unroll") for (int _i = 0; _i < 2; ++_i) \
;         __builtin_amdgcn_global_load_lds((const unsigned*)((const char*)(gbase) + (voff)[_i]), (PG8_LAS unsigned*)(lds + (bufoff) + ldsw + _i * 8192), 16, 0, 0); } while (0)
; #define PG8_LDA(dst, b, h) do { _Pragma("unroll") for (int m = 0; m < 4; ++m) _Pragma("unroll") for (int k = 0; k < 2; ++k) dst[m][k] = *(const PG8_LAS bf16x8*)(lds + PG8_SA(b, h) + aoff + m * 2048 + k * 1024); } while (0)
; #define PG8_MMA(ai, bj, At, Bt) do { __builtin_amdgcn_s_setprio(1); _Pragma("unroll") for (int m = 0; m < 4; ++m) _Pragma("unroll") for (int n = 0; n < 2; ++n) _Pragma("unroll") for (int k = 0; k < 2; ++k) \
;         acc[ai][bj][m][n] = __builtin_amdgcn_mfma_f32_16x16x32_bf16(Bt[n][k], At[m][k], acc[ai][bj][m][n], 0, 0, 0); __builtin_amdgcn_s_setprio(0); } while (0)
; #define PG8_WAIT_V(n) asm volatile("s_waitcnt vmcnt(" #n ")" ::: "memory")
; #define PG8_WAIT_L(n) asm volatile("s_waitcnt lgkmcnt(" #n ")" ::: "memory")
; #define PG8_BAR __builtin_amdgcn_s_barrier()
; #define PG8_SCHED __builtin_amdgcn_sched_barrier(0)
; template <class Epi, class Sched, bool ALIGN_EPI = false, bool SP2 = false>
; __device__ __forceinline__ void gemm_phase(PG8_LAS unsigned char* lds, const Gemm g, const Sched& S, const Epi& E) {
;     ...
;             PG8_LDA(At, 1, 1); PG8_STAGE(PG8_SB(1, 0), b3, voffB); PG8_STAGE(PG8_SB(1, 1), b3 + hstep, voffB); PG8_STAGE(PG8_SA(1, 0), a3, voffA);
;             PG8_WAIT_V(8); PG8_WAIT_L(0); PG8_BAR; PG8_MMA(1, 0, At, B0); PG8_MMA(1, 1, At, B1); PG8_BAR; PG8_SCHED;
;     ...
;         if constexpr (ALIGN_EPI) { if (wr == 0) PG8_BAR; }
	v_mfma_f32_16x16x32_bf16 v[66:69], v[200:203], v[244:247], v[66:69]
	s_setprio 0
	s_add_i32 s24, s48, s33
	v_lshl_add_u64 v[144:145], v[144:145], 0, s[52:53]
	s_mov_b32 m0, s24
	ds_read_b128 v[204:207], v149 offset:49152
	ds_read_b128 v[208:211], v149 offset:50176
	ds_read_b128 v[212:215], v149 offset:51200
	ds_read_b128 v[216:219], v149 offset:52224
	ds_read_b128 v[220:223], v149 offset:53248
	ds_read_b128 v[224:227], v149 offset:54272
	ds_read_b128 v[228:231], v149 offset:55296
	ds_read_b128 v[244:247], v149 offset:56320
	global_load_lds_dwordx4 v[144:145], off
	s_add_i32 m0, s24, 0x2000
	s_add_u32 s22, s22, 0x40080
	v_lshl_add_u64 v[144:145], v[232:233], 0, s[52:53]
	s_addc_u32 s23, s23, 0
	s_add_i32 s24, s49, s33
	global_load_lds_dwordx4 v[144:145], off
	v_lshl_add_u64 v[144:145], s[22:23], 0, v[0:1]
	s_mov_b32 m0, s24
	s_nop 0
	global_load_lds_dwordx4 v[144:145], off
	v_lshl_add_u64 v[144:145], s[22:23], 0, v[130:131]
	s_add_i32 m0, s24, 0x2000
	s_nop 0
	global_load_lds_dwordx4 v[144:145], off
	v_lshl_add_u64 v[144:145], v[236:237], 0, s[52:53]
	s_mov_b32 m0, s39
	s_nop 0
	global_load_lds_dwordx4 v[144:145], off
	v_lshl_add_u64 v[144:145], v[248:249], 0, s[52:53]
	s_mov_b32 m0, s40
	s_nop 0
	global_load_lds_dwordx4 v[144:145], off
	s_waitcnt vmcnt(8)
	s_waitcnt lgkmcnt(0)
	s_barrier
	s_setprio 1
	s_waitcnt lgkmcnt(0)
	v_mfma_f32_16x16x32_bf16 v[62:65], v[140:143], v[204:207], v[62:65]
	v_mfma_f32_16x16x32_bf16 v[58:61], v[154:157], v[204:207], v[58:61]
	v_mfma_f32_16x16x32_bf16 v[46:49], v[140:143], v[212:215], v[46:49]
	v_mfma_f32_16x16x32_bf16 v[42:45], v[154:157], v[212:215], v[42:45]
	v_mfma_f32_16x16x32_bf16 v[30:33], v[140:143], v[220:223], v[30:33]
	v_mfma_f32_16x16x32_bf16 v[26:29], v[154:157], v[220:223], v[26:29]
	v_mfma_f32_16x16x32_bf16 v[14:17], v[140:143], v[228:231], v[14:17]
	v_mfma_f32_16x16x32_bf16 v[10:13], v[154:157], v[228:231], v[10:13]
	v_mfma_f32_16x16x32_bf16 v[62:65], v[150:153], v[208:211], v[62:65]
	v_mfma_f32_16x16x32_bf16 v[58:61], v[158:161], v[208:211], v[58:61]
	v_mfma_f32_16x16x32_bf16 v[46:49], v[150:153], v[216:219], v[46:49]
	v_mfma_f32_16x16x32_bf16 v[42:45], v[158:161], v[216:219], v[42:45]
	v_mfma_f32_16x16x32_bf16 v[30:33], v[150:153], v[224:227], v[30:33]
	v_mfma_f32_16x16x32_bf16 v[26:29], v[158:161], v[224:227], v[26:29]
	v_mfma_f32_16x16x32_bf16 v[14:17], v[150:153], v[244:247], v[14:17]
	v_mfma_f32_16x16x32_bf16 v[10:13], v[158:161], v[244:247], v[10:13]
	s_setprio 0
	s_setprio 1
	v_mfma_f32_16x16x32_bf16 v[54:57], v[162:165], v[204:207], v[54:57]
	v_mfma_f32_16x16x32_bf16 v[50:53], v[196:199], v[204:207], v[50:53]
	v_mfma_f32_16x16x32_bf16 v[38:41], v[162:165], v[212:215], v[38:41]
	v_mfma_f32_16x16x32_bf16 v[34:37], v[196:199], v[212:215], v[34:37]
	v_mfma_f32_16x16x32_bf16 v[22:25], v[162:165], v[220:223], v[22:25]
	v_mfma_f32_16x16x32_bf16 v[18:21], v[196:199], v[220:223], v[18:21]
	v_mfma_f32_16x16x32_bf16 v[6:9], v[162:165], v[228:231], v[6:9]
	v_mfma_f32_16x16x32_bf16 v[2:5], v[196:199], v[228:231], v[2:5]
	v_mfma_f32_16x16x32_bf16 v[54:57], v[192:195], v[208:211], v[54:57]
	v_mfma_f32_16x16x32_bf16 v[50:53], v[200:203], v[208:211], v[50:53]
	v_mfma_f32_16x16x32_bf16 v[38:41], v[192:195], v[216:219], v[38:41]
	v_mfma_f32_16x16x32_bf16 v[34:37], v[200:203], v[216:219], v[34:37]
	v_mfma_f32_16x16x32_bf16 v[22:25], v[192:195], v[224:227], v[22:25]
	v_mfma_f32_16x16x32_bf16 v[18:21], v[200:203], v[224:227], v[18:21]
	v_mfma_f32_16x16x32_bf16 v[6:9], v[192:195], v[244:247], v[6:9]
	s_setprio 3
	s_barrier
	v_mfma_f32_16x16x32_bf16 v[2:5], v[200:203], v[244:247], v[2:5]
	s_setprio 0
	s_add_i32 s47, s47, 2
	s_add_u32 s45, s45, 0x100
	s_addc_u32 s46, s46, 0
	s_add_u32 s20, s20, 0x100
	s_addc_u32 s21, s21, 0
	s_cmp_gt_u32 s47, 13
	s_cbranch_scc0 .LBB0_752
	s_and_b64 vcc, exec, s[8:9]
	s_cbranch_vccz .LBB0_755
	s_barrier

; #define PG8_STAGE(bufoff, gbase, voff) do { _Pragma("unroll") for (int _i = 0; _i < 2; ++_i) \
;         __builtin_amdgcn_global_load_lds((const unsigned*)((const char*)(gbase) + (voff)[_i]), (PG8_LAS unsigned*)(lds + (bufoff) + ldsw + _i * 8192), 16, 0, 0); } while (0)
; #define PG8_LDA(dst, b, h) do { _Pragma("unroll") for (int m = 0; m < 4; ++m) _Pragma("unroll") for (int k = 0; k < 2; ++k) dst[m][k] = *(const PG8_LAS bf16x8*)(lds + PG8_SA(b, h) + aoff + m * 2048 + k * 1024); } while (0)
; #define PG8_LDB(dst, b, h) do { _Pragma("unroll") for (int n = 0; n < 2; ++n) _Pragma("unroll") for (int k = 0; k < 2; ++k) dst[n][k] = *(const PG8_LAS bf16x8*)(lds + PG8_SB(b, h) + boff + n * 2048 + k * 1024); } while (0)
; #define PG8_MMA(ai, bj, At, Bt) do { __builtin_amdgcn_s_setprio(1); _Pragma("unroll") for (int m = 0; m < 4; ++m) _Pragma("unroll") for (int n = 0; n < 2; ++n) _Pragma("unroll") for (int k = 0; k < 2; ++k) \
;         acc[ai][bj][m][n] = __builtin_amdgcn_mfma_f32_16x16x32_bf16(Bt[n][k], At[m][k], acc[ai][bj][m][n], 0, 0, 0); __builtin_amdgcn_s_setprio(0); } while (0)
; #define PG8_WAIT_V(n) asm volatile("s_waitcnt vmcnt(" #n ")" ::: "memory")
; #define PG8_BAR __builtin_amdgcn_s_barrier()
; template <class Epi, class Sched, bool ALIGN_EPI = false, bool SP2 = false>
; __device__ __forceinline__ void gemm_phase(PG8_LAS unsigned char* lds, const Gemm g, const Sched& S, const Epi& E) {
;     ...
;         for (int t = 0; t < nt; t += 2) {
;             const bool last = (t == nt - 2);
;             const char* a1 = cA + (size_t)(t + 1) * kstep;
;             const char* a2 = last ? nA : cA + (size_t)(t + 2) * kstep; const char* b2 = last ? nB : cB + (size_t)(t + 2) * kstep;
;             const char* a3 = a2 + kstep; const char* b3 = b2 + kstep;
;             if (last && has_next) S.a_ready(nxt);
;             if constexpr (SP2) {
;             PG8_LDB(B0, 0, 0); PG8_LDB(B1, 0, 1); PG8_SCHED; PG8_LDA(At, 0, 0); PG8_STAGE(PG8_SA(1, 1), a1 + hstep, voffA);
;             PG8_WAIT_V(8); PG8_WAIT_L(0); PG8_BAR; PG8_MMA(0, 0, At, B0); PG8_MMA(0, 1, At, B1); PG8_BAR; PG8_SCHED;
;             PG8_LDA(At, 0, 1); PG8_STAGE(PG8_SB(0, 0), b2, voffB); PG8_STAGE(PG8_SB(0, 1), b2 + hstep, voffB); PG8_STAGE(PG8_SA(0, 0), a2, voffA);
;             PG8_WAIT_V(8); PG8_WAIT_L(0); PG8_BAR; PG8_MMA(1, 0, At, B0); PG8_MMA(1, 1, At, B1); PG8_BAR; PG8_SCHED;
.LBB0_839:
	s_add_u32 s22, s10, 0x100
	s_addc_u32 s23, s11, 0
	s_add_i32 s53, 0, 0x10000
	s_cmp_eq_u32 s52, 40
	s_cselect_b32 s27, s1, s23
	s_cselect_b32 s26, s0, s22
	s_cselect_b32 s25, s21, s51
	s_cselect_b32 s24, s20, s50
	s_add_i32 s54, 0, 0x14000
	v_add_u32_e32 v156, s53, v149
	v_add_u32_e32 v164, s54, v149
	ds_read_b128 v[140:143], v156
	ds_read_b128 v[144:147], v156 offset:1024
	ds_read_b128 v[152:155], v156 offset:2048
	ds_read_b128 v[156:159], v156 offset:3072
	ds_read_b128 v[160:163], v164
	ds_read_b128 v[192:195], v164 offset:1024
	ds_read_b128 v[196:199], v164 offset:2048
	ds_read_b128 v[200:203], v164 offset:3072
	v_lshl_add_u64 v[164:165], s[10:11], 0, v[138:139]
	s_add_i32 m0, s36, 0xc000
	ds_read_b128 v[204:207], v151
	ds_read_b128 v[208:211], v151 offset:1024
	ds_read_b128 v[212:215], v151 offset:2048
	ds_read_b128 v[216:219], v151 offset:3072
	ds_read_b128 v[220:223], v151 offset:4096
	ds_read_b128 v[224:227], v151 offset:5120
	ds_read_b128 v[228:231], v151 offset:6144
	ds_read_b128 v[244:247], v151 offset:7168
	global_load_lds_dwordx4 v[164:165], off
	v_lshl_add_u64 v[164:165], s[10:11], 0, v[136:137]
	s_add_i32 m0, s36, 0xe000
	s_nop 0
	global_load_lds_dwordx4 v[164:165], off
	s_waitcnt vmcnt(8)
	s_waitcnt lgkmcnt(0)
	s_barrier
	s_setprio 1
	s_waitcnt lgkmcnt(0)
	v_mfma_f32_16x16x32_bf16 v[126:129], v[140:143], v[204:207], v[126:129]
	v_mfma_f32_16x16x32_bf16 v[122:125], v[152:155], v[204:207], v[122:125]
	v_mfma_f32_16x16x32_bf16 v[110:113], v[140:143], v[212:215], v[110:113]
	v_mfma_f32_16x16x32_bf16 v[106:109], v[152:155], v[212:215], v[106:109]
	v_mfma_f32_16x16x32_bf16 v[94:97], v[140:143], v[220:223], v[94:97]
	v_mfma_f32_16x16x32_bf16 v[90:93], v[152:155], v[220:223], v[90:93]
	v_mfma_f32_16x16x32_bf16 v[78:81], v[140:143], v[228:231], v[78:81]
	v_mfma_f32_16x16x32_bf16 v[74:77], v[152:155], v[228:231], v[74:77]
	v_mfma_f32_16x16x32_bf16 v[126:129], v[144:147], v[208:211], v[126:129]
	v_mfma_f32_16x16x32_bf16 v[122:125], v[156:159], v[208:211], v[122:125]
	v_mfma_f32_16x16x32_bf16 v[110:113], v[144:147], v[216:219], v[110:113]
	v_mfma_f32_16x16x32_bf16 v[106:109], v[156:159], v[216:219], v[106:109]
	v_mfma_f32_16x16x32_bf16 v[94:97], v[144:147], v[224:227], v[94:97]
	v_mfma_f32_16x16x32_bf16 v[90:93], v[156:159], v[224:227], v[90:93]
	v_mfma_f32_16x16x32_bf16 v[78:81], v[144:147], v[244:247], v[78:81]
	v_mfma_f32_16x16x32_bf16 v[74:77], v[156:159], v[244:247], v[74:77]
	s_setprio 0
	s_setprio 1
	v_mfma_f32_16x16x32_bf16 v[118:121], v[160:163], v[204:207], v[118:121]
	v_mfma_f32_16x16x32_bf16 v[114:117], v[196:199], v[204:207], v[114:117]
	v_mfma_f32_16x16x32_bf16 v[102:105], v[160:163], v[212:215], v[102:105]
	v_mfma_f32_16x16x32_bf16 v[98:101], v[196:199], v[212:215], v[98:101]
	v_mfma_f32_16x16x32_bf16 v[86:89], v[160:163], v[220:223], v[86:89]
	v_mfma_f32_16x16x32_bf16 v[82:85], v[196:199], v[220:223], v[82:85]
	v_mfma_f32_16x16x32_bf16 v[70:73], v[160:163], v[228:231], v[70:73]
	v_mfma_f32_16x16x32_bf16 v[66:69], v[196:199], v[228:231], v[66:69]
	v_mfma_f32_16x16x32_bf16 v[118:121], v[192:195], v[208:211], v[118:121]
	v_mfma_f32_16x16x32_bf16 v[114:117], v[200:203], v[208:211], v[114:117]
	v_mfma_f32_16x16x32_bf16 v[102:105], v[192:195], v[216:219], v[102:105]
	v_mfma_f32_16x16x32_bf16 v[98:101], v[200:203], v[216:219], v[98:101]
	v_mfma_f32_16x16x32_bf16 v[86:89], v[192:195], v[224:227], v[86:89]
	v_mfma_f32_16x16x32_bf16 v[82:85], v[200:203], v[224:227], v[82:85]
	v_mfma_f32_16x16x32_bf16 v[70:73], v[192:195], v[244:247], v[70:73]
	s_setprio 3
	s_barrier
	v_mfma_f32_16x16x32_bf16 v[66:69], v[200:203], v[244:247], v[66:69]
	s_setprio 0
	s_add_i32 s10, s53, s30
	v_lshl_add_u64 v[164:165], s[24:25], 0, v[0:1]
	s_mov_b32 m0, s10
	ds_read_b128 v[204:207], v151 offset:16384
	ds_read_b128 v[208:211], v151 offset:17408
	ds_read_b128 v[212:215], v151 offset:18432
	ds_read_b128 v[216:219], v151 offset:19456
	ds_read_b128 v[220:223], v151 offset:20480
	ds_read_b128 v[224:227], v151 offset:21504
	ds_read_b128 v[228:231], v151 offset:22528
	ds_read_b128 v[244:247], v151 offset:23552
	global_load_lds_dwordx4 v[164:165], off
	s_add_i32 m0, s10, 0x2000
	s_add_u32 s10, s24, 0xb0000
	v_lshl_add_u64 v[232:233], s[24:25], 0, v[134:135]
	s_addc_u32 s11, s25, 0
	s_add_i32 s53, s54, s30
	global_load_lds_dwordx4 v[232:233], off
	v_lshl_add_u64 v[236:237], s[10:11], 0, v[0:1]
	s_mov_b32 m0, s53
	v_lshl_add_u64 v[248:249], s[26:27], 0, v[132:133]
	global_load_lds_dwordx4 v[236:237], off
	v_lshl_add_u64 v[236:237], s[10:11], 0, v[134:135]
	s_add_i32 m0, s53, 0x2000
	s_nop 0
	global_load_lds_dwordx4 v[236:237], off
	v_lshl_add_u64 v[236:237], s[26:27], 0, v[130:131]
	s_mov_b32 m0, s36
	s_nop 0
	global_load_lds_dwordx4 v[236:237], off
	s_mov_b32 m0, s37
	s_nop 0
	global_load_lds_dwordx4 v[248:249], off
	s_waitcnt vmcnt(8)
	s_waitcnt lgkmcnt(0)
	s_barrier
; #define PG8_STAGE(bufoff, gbase, voff) do { _Pragma("unroll") for (int _i = 0; _i < 2; ++_i) \
;         __builtin_amdgcn_global_load_lds((const unsigned*)((const char*)(gbase) + (voff)[_i]), (PG8_LAS unsigned*)(lds + (bufoff) + ldsw + _i * 8192), 16, 0, 0); } while (0)
; #define PG8_LDA(dst, b, h) do { _Pragma("unroll") for (int m = 0; m < 4; ++m) _Pragma("unroll") for (int k = 0; k < 2; ++k) dst[m][k] = *(const PG8_LAS bf16x8*)(lds + PG8_SA(b, h) + aoff + m * 2048 + k * 1024); } while (0)
; #define PG8_LDB(dst, b, h) do { _Pragma("unroll") for (int n = 0; n < 2; ++n) _Pragma("unroll") for (int k = 0; k < 2; ++k) dst[n][k] = *(const PG8_LAS bf16x8*)(lds + PG8_SB(b, h) + boff + n * 2048 + k * 1024); } while (0)
; #define PG8_MMA(ai, bj, At, Bt) do { __builtin_amdgcn_s_setprio(1); _Pragma("unroll") for (int m = 0; m < 4; ++m) _Pragma("unroll") for (int n = 0; n < 2; ++n) _Pragma("unroll") for (int k = 0; k < 2; ++k) \
;         acc[ai][bj][m][n] = __builtin_amdgcn_mfma_f32_16x16x32_bf16(Bt[n][k], At[m][k], acc[ai][bj][m][n], 0, 0, 0); __builtin_amdgcn_s_setprio(0); } while (0)
; #define PG8_WAIT_V(n) asm volatile("s_waitcnt vmcnt(" #n ")" ::: "memory")
; #define PG8_WAIT_L(n) asm volatile("s_waitcnt lgkmcnt(" #n ")" ::: "memory")
; #define PG8_BAR __builtin_amdgcn_s_barrier()
; #define PG8_SCHED __builtin_amdgcn_sched_barrier(0)
; template <class Epi, class Sched, bool ALIGN_EPI = false, bool SP2 = false>
; __device__ __forceinline__ void gemm_phase(PG8_LAS unsigned char* lds, const Gemm g, const Sched& S, const Epi& E) {
;     ...
;             PG8_WAIT_V(8); PG8_WAIT_L(0); PG8_BAR; PG8_MMA(0, 0, At, B0); PG8_MMA(0, 1, At, B1); PG8_BAR; PG8_SCHED;
;             PG8_LDA(At, 0, 1); PG8_STAGE(PG8_SB(0, 0), b2, voffB); PG8_STAGE(PG8_SB(0, 1), b2 + hstep, voffB); PG8_STAGE(PG8_SA(0, 0), a2, voffA);
;             PG8_WAIT_V(8); PG8_WAIT_L(0); PG8_BAR; PG8_MMA(1, 0, At, B0); PG8_MMA(1, 1, At, B1); PG8_BAR; PG8_SCHED;
;             PG8_LDB(B0, 1, 0); PG8_LDB(B1, 1, 1); PG8_SCHED; PG8_LDA(At, 1, 0); PG8_STAGE(PG8_SA(0, 1), a2 + hstep, voffA);
;             PG8_WAIT_V(8); PG8_WAIT_L(0); PG8_BAR; PG8_MMA(0, 0, At, B0); PG8_MMA(0, 1, At, B1); PG8_BAR; PG8_SCHED;
	s_setprio 1
	s_waitcnt lgkmcnt(0)
	v_mfma_f32_16x16x32_bf16 v[62:65], v[140:143], v[204:207], v[62:65]
	v_mfma_f32_16x16x32_bf16 v[58:61], v[152:155], v[204:207], v[58:61]
	v_mfma_f32_16x16x32_bf16 v[46:49], v[140:143], v[212:215], v[46:49]
	v_mfma_f32_16x16x32_bf16 v[42:45], v[152:155], v[212:215], v[42:45]
	v_mfma_f32_16x16x32_bf16 v[30:33], v[140:143], v[220:223], v[30:33]
	v_mfma_f32_16x16x32_bf16 v[26:29], v[152:155], v[220:223], v[26:29]
	v_mfma_f32_16x16x32_bf16 v[14:17], v[140:143], v[228:231], v[14:17]
	v_mfma_f32_16x16x32_bf16 v[10:13], v[152:155], v[228:231], v[10:13]
	v_mfma_f32_16x16x32_bf16 v[62:65], v[144:147], v[208:211], v[62:65]
	v_mfma_f32_16x16x32_bf16 v[58:61], v[156:159], v[208:211], v[58:61]
	v_mfma_f32_16x16x32_bf16 v[46:49], v[144:147], v[216:219], v[46:49]
	v_mfma_f32_16x16x32_bf16 v[42:45], v[156:159], v[216:219], v[42:45]
	v_mfma_f32_16x16x32_bf16 v[30:33], v[144:147], v[224:227], v[30:33]
	v_mfma_f32_16x16x32_bf16 v[26:29], v[156:159], v[224:227], v[26:29]
	v_mfma_f32_16x16x32_bf16 v[14:17], v[144:147], v[244:247], v[14:17]
	v_mfma_f32_16x16x32_bf16 v[10:13], v[156:159], v[244:247], v[10:13]
	s_setprio 0
	s_setprio 1
	v_mfma_f32_16x16x32_bf16 v[54:57], v[160:163], v[204:207], v[54:57]
	v_mfma_f32_16x16x32_bf16 v[50:53], v[196:199], v[204:207], v[50:53]
	v_mfma_f32_16x16x32_bf16 v[38:41], v[160:163], v[212:215], v[38:41]
	v_mfma_f32_16x16x32_bf16 v[34:37], v[196:199], v[212:215], v[34:37]
	v_mfma_f32_16x16x32_bf16 v[22:25], v[160:163], v[220:223], v[22:25]
	v_mfma_f32_16x16x32_bf16 v[18:21], v[196:199], v[220:223], v[18:21]
	v_mfma_f32_16x16x32_bf16 v[6:9], v[160:163], v[228:231], v[6:9]
	v_mfma_f32_16x16x32_bf16 v[2:5], v[196:199], v[228:231], v[2:5]
	v_mfma_f32_16x16x32_bf16 v[54:57], v[192:195], v[208:211], v[54:57]
	v_mfma_f32_16x16x32_bf16 v[50:53], v[200:203], v[208:211], v[50:53]
	v_mfma_f32_16x16x32_bf16 v[38:41], v[192:195], v[216:219], v[38:41]
	v_mfma_f32_16x16x32_bf16 v[34:37], v[200:203], v[216:219], v[34:37]
	v_mfma_f32_16x16x32_bf16 v[22:25], v[192:195], v[224:227], v[22:25]
	v_mfma_f32_16x16x32_bf16 v[18:21], v[200:203], v[224:227], v[18:21]
	v_mfma_f32_16x16x32_bf16 v[6:9], v[192:195], v[244:247], v[6:9]
	s_setprio 3
	s_barrier
	v_mfma_f32_16x16x32_bf16 v[2:5], v[200:203], v[244:247], v[2:5]
	s_setprio 0
	s_add_i32 s53, 0, 0x18000
	s_add_i32 s54, 0, 0x1c000
	v_add_u32_e32 v156, s53, v149
	v_add_u32_e32 v182, s54, v149
	ds_read_b128 v[140:143], v156
	ds_read_b128 v[144:147], v156 offset:1024
	ds_read_b128 v[152:155], v156 offset:2048
	ds_read_b128 v[156:159], v156 offset:3072
	ds_read_b128 v[160:163], v182
	ds_read_b128 v[192:195], v182 offset:1024
	ds_read_b128 v[196:199], v182 offset:2048
	ds_read_b128 v[200:203], v182 offset:3072
	s_add_u32 s10, s26, 0xb0000
	s_addc_u32 s11, s27, 0
	s_mov_b32 m0, s38
	v_lshl_add_u64 v[250:251], s[10:11], 0, v[130:131]
	ds_read_b128 v[204:207], v151 offset:32768
	ds_read_b128 v[208:211], v151 offset:33792
	ds_read_b128 v[212:215], v151 offset:34816
	ds_read_b128 v[216:219], v151 offset:35840
	ds_read_b128 v[220:223], v151 offset:36864
	ds_read_b128 v[224:227], v151 offset:37888
	ds_read_b128 v[228:231], v151 offset:38912
	ds_read_b128 v[244:247], v151 offset:39936
	global_load_lds_dwordx4 v[250:251], off
	v_lshl_add_u64 v[250:251], s[10:11], 0, v[132:133]
	s_mov_b32 m0, s39
	s_nop 0
	global_load_lds_dwordx4 v[250:251], off
	s_waitcnt vmcnt(8)
	s_waitcnt lgkmcnt(0)
	s_barrier
	s_setprio 1
	s_waitcnt lgkmcnt(0)
	v_mfma_f32_16x16x32_bf16 v[126:129], v[140:143], v[204:207], v[126:129]
	v_mfma_f32_16x16x32_bf16 v[122:125], v[152:155], v[204:207], v[122:125]
	v_mfma_f32_16x16x32_bf16 v[110:113], v[140:143], v[212:215], v[110:113]
	v_mfma_f32_16x16x32_bf16 v[106:109], v[152:155], v[212:215], v[106:109]
	v_mfma_f32_16x16x32_bf16 v[94:97], v[140:143], v[220:223], v[94:97]
	v_mfma_f32_16x16x32_bf16 v[90:93], v[152:155], v[220:223], v[90:93]
	v_mfma_f32_16x16x32_bf16 v[78:81], v[140:143], v[228:231], v[78:81]
	v_mfma_f32_16x16x32_bf16 v[74:77], v[152:155], v[228:231], v[74:77]
	v_mfma_f32_16x16x32_bf16 v[126:129], v[144:147], v[208:211], v[126:129]
	v_mfma_f32_16x16x32_bf16 v[122:125], v[156:159], v[208:211], v[122:125]
	v_mfma_f32_16x16x32_bf16 v[110:113], v[144:147], v[216:219], v[110:113]
	v_mfma_f32_16x16x32_bf16 v[106:109], v[156:159], v[216:219], v[106:109]
	v_mfma_f32_16x16x32_bf16 v[94:97], v[144:147], v[224:227], v[94:97]
	v_mfma_f32_16x16x32_bf16 v[90:93], v[156:159], v[224:227], v[90:93]
	v_mfma_f32_16x16x32_bf16 v[78:81], v[144:147], v[244:247], v[78:81]
	v_mfma_f32_16x16x32_bf16 v[74:77], v[156:159], v[244:247], v[74:77]
	s_setprio 0
	s_setprio 1
	v_mfma_f32_16x16x32_bf16 v[118:121], v[160:163], v[204:207], v[118:121]
	v_mfma_f32_16x16x32_bf16 v[114:117], v[196:199], v[204:207], v[114:117]
	v_mfma_f32_16x16x32_bf16 v[102:105], v[160:163], v[212:215], v[102:105]
	v_mfma_f32_16x16x32_bf16 v[98:101], v[196:199], v[212:215], v[98:101]
	v_mfma_f32_16x16x32_bf16 v[86:89], v[160:163], v[220:223], v[86:89]
	v_mfma_f32_16x16x32_bf16 v[82:85], v[196:199], v[220:223], v[82:85]
	v_mfma_f32_16x16x32_bf16 v[70:73], v[160:163], v[228:231], v[70:73]
	v_mfma_f32_16x16x32_bf16 v[66:69], v[196:199], v[228:231], v[66:69]
	v_mfma_f32_16x16x32_bf16 v[118:121], v[192:195], v[208:211], v[118:121]
	v_mfma_f32_16x16x32_bf16 v[114:117], v[200:203], v[208:211], v[114:117]
	v_mfma_f32_16x16x32_bf16 v[102:105], v[192:195], v[216:219], v[102:105]
	v_mfma_f32_16x16x32_bf16 v[98:101], v[200:203], v[216:219], v[98:101]
	v_mfma_f32_16x16x32_bf16 v[86:89], v[192:195], v[224:227], v[86:89]
	v_mfma_f32_16x16x32_bf16 v[82:85], v[200:203], v[224:227], v[82:85]
	v_mfma_f32_16x16x32_bf16 v[70:73], v[192:195], v[244:247], v[70:73]
	s_setprio 3
	s_barrier
; #define PG8_STAGE(bufoff, gbase, voff) do { _Pragma("unroll") for (int _i = 0; _i < 2; ++_i) \
;         __builtin_amdgcn_global_load_lds((const unsigned*)((const char*)(gbase) + (voff)[_i]), (PG8_LAS unsigned*)(lds + (bufoff) + ldsw + _i * 8192), 16, 0, 0); } while (0)
; #define PG8_LDA(dst, b, h) do { _Pragma("unroll") for (int m = 0; m < 4; ++m) _Pragma("unroll") for (int k = 0; k < 2; ++k) dst[m][k] = *(const PG8_LAS bf16x8*)(lds + PG8_SA(b, h) + aoff + m * 2048 + k * 1024); } while (0)
; #define PG8_MMA(ai, bj, At, Bt) do { __builtin_amdgcn_s_setprio(1); _Pragma("unroll") for (int m = 0; m < 4; ++m) _Pragma("unroll") for (int n = 0; n < 2; ++n) _Pragma("unroll") for (int k = 0; k < 2; ++k) \
;         acc[ai][bj][m][n] = __builtin_amdgcn_mfma_f32_16x16x32_bf16(Bt[n][k], At[m][k], acc[ai][bj][m][n], 0, 0, 0); __builtin_amdgcn_s_setprio(0); } while (0)
; #define PG8_WAIT_V(n) asm volatile("s_waitcnt vmcnt(" #n ")" ::: "memory")
; #define PG8_WAIT_L(n) asm volatile("s_waitcnt lgkmcnt(" #n ")" ::: "memory")
; #define PG8_BAR __builtin_amdgcn_s_barrier()
; #define PG8_SCHED __builtin_amdgcn_sched_barrier(0)
; template <class Epi, class Sched, bool ALIGN_EPI = false, bool SP2 = false>
; __device__ __forceinline__ void gemm_phase(PG8_LAS unsigned char* lds, const Gemm g, const Sched& S, const Epi& E) {
;     ...
;         for (int t = 0; t < nt; t += 2) {
;     ...
;             PG8_WAIT_V(8); PG8_WAIT_L(0); PG8_BAR; PG8_MMA(0, 0, At, B0); PG8_MMA(0, 1, At, B1); PG8_BAR; PG8_SCHED;
;             PG8_LDA(At, 1, 1); PG8_STAGE(PG8_SB(1, 0), b3, voffB); PG8_STAGE(PG8_SB(1, 1), b3 + hstep, voffB); PG8_STAGE(PG8_SA(1, 0), a3, voffA);
;             PG8_WAIT_V(8); PG8_WAIT_L(0); PG8_BAR; PG8_MMA(1, 0, At, B0); PG8_MMA(1, 1, At, B1); PG8_BAR; PG8_SCHED;
	v_mfma_f32_16x16x32_bf16 v[66:69], v[200:203], v[244:247], v[66:69]
	s_setprio 0
	s_add_i32 s10, s53, s30
	v_lshl_add_u64 v[164:165], v[164:165], 0, s[56:57]
	s_mov_b32 m0, s10
	ds_read_b128 v[204:207], v151 offset:49152
	ds_read_b128 v[208:211], v151 offset:50176
	ds_read_b128 v[212:215], v151 offset:51200
	ds_read_b128 v[216:219], v151 offset:52224
	ds_read_b128 v[220:223], v151 offset:53248
	ds_read_b128 v[224:227], v151 offset:54272
	ds_read_b128 v[228:231], v151 offset:55296
	ds_read_b128 v[244:247], v151 offset:56320
	global_load_lds_dwordx4 v[164:165], off
	s_add_i32 m0, s10, 0x2000
	s_add_u32 s10, s24, 0xb0080
	v_lshl_add_u64 v[164:165], v[232:233], 0, s[56:57]
	s_addc_u32 s11, s25, 0
	s_add_i32 s24, s54, s30
	global_load_lds_dwordx4 v[164:165], off
	v_lshl_add_u64 v[164:165], s[10:11], 0, v[0:1]
	s_mov_b32 m0, s24
	s_nop 0
	global_load_lds_dwordx4 v[164:165], off
	v_lshl_add_u64 v[164:165], s[10:11], 0, v[134:135]
	s_add_i32 m0, s24, 0x2000
	s_nop 0
	global_load_lds_dwordx4 v[164:165], off
	v_lshl_add_u64 v[164:165], v[236:237], 0, s[56:57]
	s_mov_b32 m0, s41
	s_nop 0
	global_load_lds_dwordx4 v[164:165], off
	v_lshl_add_u64 v[164:165], v[248:249], 0, s[56:57]
	s_mov_b32 m0, s42
	s_nop 0
	global_load_lds_dwordx4 v[164:165], off
	s_waitcnt vmcnt(8)
	s_waitcnt lgkmcnt(0)
	s_barrier
	s_setprio 1
	s_waitcnt lgkmcnt(0)
	v_mfma_f32_16x16x32_bf16 v[62:65], v[140:143], v[204:207], v[62:65]
	v_mfma_f32_16x16x32_bf16 v[58:61], v[152:155], v[204:207], v[58:61]
	v_mfma_f32_16x16x32_bf16 v[46:49], v[140:143], v[212:215], v[46:49]
	v_mfma_f32_16x16x32_bf16 v[42:45], v[152:155], v[212:215], v[42:45]
	v_mfma_f32_16x16x32_bf16 v[30:33], v[140:143], v[220:223], v[30:33]
	v_mfma_f32_16x16x32_bf16 v[26:29], v[152:155], v[220:223], v[26:29]
	v_mfma_f32_16x16x32_bf16 v[14:17], v[140:143], v[228:231], v[14:17]
	v_mfma_f32_16x16x32_bf16 v[10:13], v[152:155], v[228:231], v[10:13]
	v_mfma_f32_16x16x32_bf16 v[62:65], v[144:147], v[208:211], v[62:65]
	v_mfma_f32_16x16x32_bf16 v[58:61], v[156:159], v[208:211], v[58:61]
	v_mfma_f32_16x16x32_bf16 v[46:49], v[144:147], v[216:219], v[46:49]
	v_mfma_f32_16x16x32_bf16 v[42:45], v[156:159], v[216:219], v[42:45]
	v_mfma_f32_16x16x32_bf16 v[30:33], v[144:147], v[224:227], v[30:33]
	v_mfma_f32_16x16x32_bf16 v[26:29], v[156:159], v[224:227], v[26:29]
	v_mfma_f32_16x16x32_bf16 v[14:17], v[144:147], v[244:247], v[14:17]
	v_mfma_f32_16x16x32_bf16 v[10:13], v[156:159], v[244:247], v[10:13]
	s_setprio 0
	s_setprio 1
	v_mfma_f32_16x16x32_bf16 v[54:57], v[160:163], v[204:207], v[54:57]
	v_mfma_f32_16x16x32_bf16 v[50:53], v[196:199], v[204:207], v[50:53]
	v_mfma_f32_16x16x32_bf16 v[38:41], v[160:163], v[212:215], v[38:41]
	v_mfma_f32_16x16x32_bf16 v[34:37], v[196:199], v[212:215], v[34:37]
	v_mfma_f32_16x16x32_bf16 v[22:25], v[160:163], v[220:223], v[22:25]
	v_mfma_f32_16x16x32_bf16 v[18:21], v[196:199], v[220:223], v[18:21]
	v_mfma_f32_16x16x32_bf16 v[6:9], v[160:163], v[228:231], v[6:9]
	v_mfma_f32_16x16x32_bf16 v[2:5], v[196:199], v[228:231], v[2:5]
	v_mfma_f32_16x16x32_bf16 v[54:57], v[192:195], v[208:211], v[54:57]
	v_mfma_f32_16x16x32_bf16 v[50:53], v[200:203], v[208:211], v[50:53]
	v_mfma_f32_16x16x32_bf16 v[38:41], v[192:195], v[216:219], v[38:41]
	v_mfma_f32_16x16x32_bf16 v[34:37], v[200:203], v[216:219], v[34:37]
	v_mfma_f32_16x16x32_bf16 v[22:25], v[192:195], v[224:227], v[22:25]
	v_mfma_f32_16x16x32_bf16 v[18:21], v[200:203], v[224:227], v[18:21]
	v_mfma_f32_16x16x32_bf16 v[6:9], v[192:195], v[244:247], v[6:9]
	s_setprio 3
	s_barrier
	v_mfma_f32_16x16x32_bf16 v[2:5], v[200:203], v[244:247], v[2:5]
	s_setprio 0
	s_add_i32 s52, s52, 2
	s_add_u32 s50, s50, 0x100
	s_addc_u32 s51, s51, 0
	s_cmp_gt_u32 s52, 41
	s_mov_b64 s[10:11], s[22:23]
	s_cbranch_scc0 .LBB0_839
	s_and_b64 vcc, exec, s[16:17]
	s_cbranch_vccz .LBB0_842
	s_barrier
